# all P0/P1/P2 global stores sc1 (write-through) and the XCD leader's buffer_wbl2 dropped from grid barriers 1-3
# baseline (speedup 1.0000x reference)
.LBB0_17:
	s_load_dwordx16 s[36:51], s[0:1], 0x40
	s_cmp_eq_u32 s2, 0
	s_cselect_b64 s[0:1], -1, 0
	s_cmp_lt_u32 s56, 64
	s_cselect_b64 s[4:5], -1, 0
	v_mov_b32_e32 v6, v254
	s_and_b64 s[0:1], s[0:1], s[4:5]
	s_andn2_b64 vcc, exec, s[0:1]
	v_and_b32_e32 v1, 63, v6
	s_cbranch_vccnz .LBB0_19
	v_lshlrev_b32_e32 v2, 2, v1
	s_waitcnt lgkmcnt(0)
	global_load_dword v0, v2, s[20:21]
	v_mov_b32_e32 v3, 0
	v_lshl_add_u64 v[4:5], s[52:53], 0, v[2:3]
	v_add_co_u32_e32 v8, vcc, 0x10000, v4
	s_mov_b64 s[0:1], 0x10000
	s_nop 0
	v_addc_co_u32_e32 v9, vcc, 0, v5, vcc
	v_lshl_add_u64 v[4:5], v[4:5], 0, s[0:1]
	s_waitcnt vmcnt(0)
	v_mul_f32_e32 v0, 0x3e38aa3b, v0
	global_store_dword v[8:9], v0, off sc1
	global_load_dword v0, v2, s[22:23]
	s_waitcnt vmcnt(0)
	global_store_dword v[4:5], v0, off offset:256 sc1
	global_load_dword v0, v2, s[42:43]
	s_waitcnt vmcnt(0)
	v_mul_f32_e32 v0, 0x3e38aa3b, v0
	global_store_dword v[4:5], v0, off offset:512 sc1
	global_load_dword v0, v2, s[44:45]
	s_waitcnt vmcnt(0)
	global_store_dword v[4:5], v0, off offset:768 sc1

.LBB0_22:
	s_cmpk_gt_i32 s65, 0x7ff
	s_mov_b64 s[18:19], -1
	s_cbranch_scc0 .LBB0_34
	s_cmpk_gt_u32 s65, 0x9ff
	s_cbranch_scc0 .LBB0_31
	s_cmpk_gt_u32 s65, 0xbff
	s_cbranch_scc0 .LBB0_26
	s_and_b32 s0, s65, 31
	s_and_b32 s18, s60, 0x1c0
	v_or_b32_e32 v2, s18, v52
	s_lshl_b32 s0, s0, 7
	v_lshl_add_u64 v[20:21], v[4:5], 0, s[0:1]
	v_lshlrev_b32_e32 v2, 12, v2
	v_lshl_add_u64 v[20:21], v[20:21], 0, v[2:3]
	v_add_co_u32_e32 v22, vcc, 0x2000, v20
	s_lshl_b32 s0, s65, 5
	s_nop 0
	v_addc_co_u32_e32 v23, vcc, 0, v21, vcc
	v_add_co_u32_e32 v24, vcc, 0x4000, v20
	s_lshl_b32 s44, s65, 7
	s_nop 0
	v_addc_co_u32_e32 v25, vcc, 0, v21, vcc
	v_add_co_u32_e32 v26, vcc, 0x6000, v20
	s_lshl_b32 s19, s65, 4
	s_nop 0
	v_addc_co_u32_e32 v27, vcc, 0, v21, vcc
	v_add_co_u32_e32 v28, vcc, 0x8000, v20
	s_and_b32 s0, s0, 0x300
	s_nop 0
	v_addc_co_u32_e32 v29, vcc, 0, v21, vcc
	v_add_co_u32_e32 v30, vcc, 0xa000, v20
	s_and_b32 s44, s44, 0x80
	s_nop 0
	v_addc_co_u32_e32 v31, vcc, 0, v21, vcc
	v_add_co_u32_e32 v32, vcc, 0xc000, v20
	s_and_b32 s19, s19, 0x60
	s_nop 0
	v_addc_co_u32_e32 v33, vcc, 0, v21, vcc
	v_add_co_u32_e32 v34, vcc, 0xe000, v20
	s_or_b32 s0, s44, s0
	s_nop 0
	v_addc_co_u32_e32 v35, vcc, 0, v21, vcc
	global_load_dword v2, v[20:21], off nt
	global_load_dword v38, v[22:23], off nt
	global_load_dword v39, v[24:25], off nt
	global_load_dword v40, v[26:27], off nt
	global_load_dword v41, v[28:29], off nt
	global_load_dword v42, v[30:31], off nt
	global_load_dword v43, v[32:33], off nt
	global_load_dword v44, v[34:35], off nt
	v_add_co_u32_e32 v22, vcc, 0x10000, v20
	s_or_b32 s0, s0, s19
	s_nop 0
	v_addc_co_u32_e32 v23, vcc, 0, v21, vcc
	v_add_co_u32_e32 v24, vcc, 0x12000, v20
	s_nop 1
	v_addc_co_u32_e32 v25, vcc, 0, v21, vcc
	v_add_co_u32_e32 v26, vcc, 0x14000, v20
	s_nop 1
	v_addc_co_u32_e32 v27, vcc, 0, v21, vcc
	v_add_co_u32_e32 v28, vcc, 0x16000, v20
	s_nop 1
	v_addc_co_u32_e32 v29, vcc, 0, v21, vcc
	v_add_co_u32_e32 v30, vcc, 0x18000, v20
	s_nop 1
	v_addc_co_u32_e32 v31, vcc, 0, v21, vcc
	v_add_co_u32_e32 v32, vcc, 0x1a000, v20
	s_nop 1
	v_addc_co_u32_e32 v33, vcc, 0, v21, vcc
	v_add_co_u32_e32 v34, vcc, 0x1c000, v20
	s_nop 1
	v_addc_co_u32_e32 v35, vcc, 0, v21, vcc
	v_add_co_u32_e32 v36, vcc, 0x1e000, v20
	s_nop 1
	v_addc_co_u32_e32 v37, vcc, 0, v21, vcc
	global_load_dword v45, v[22:23], off nt
	global_load_dword v46, v[24:25], off nt
	global_load_dword v47, v[26:27], off nt
	global_load_dword v48, v[28:29], off nt
	global_load_dword v49, v[30:31], off nt
	global_load_dword v50, v[32:33], off nt
	global_load_dword v51, v[34:35], off nt
	global_load_dword v63, v[36:37], off nt
	v_add_co_u32_e32 v22, vcc, 0x20000, v20
	s_nop 1
	v_addc_co_u32_e32 v23, vcc, 0, v21, vcc
	v_add_co_u32_e32 v24, vcc, 0x22000, v20
	s_nop 1
	v_addc_co_u32_e32 v25, vcc, 0, v21, vcc
	v_add_co_u32_e32 v26, vcc, 0x24000, v20
	s_nop 1
	v_addc_co_u32_e32 v27, vcc, 0, v21, vcc
	v_add_co_u32_e32 v28, vcc, 0x26000, v20
	s_nop 1
	v_addc_co_u32_e32 v29, vcc, 0, v21, vcc
	v_add_co_u32_e32 v30, vcc, 0x28000, v20
	s_nop 1
	v_addc_co_u32_e32 v31, vcc, 0, v21, vcc
	v_add_co_u32_e32 v32, vcc, 0x2a000, v20
	s_nop 1
	v_addc_co_u32_e32 v33, vcc, 0, v21, vcc
	v_add_co_u32_e32 v34, vcc, 0x2c000, v20
	s_nop 1
	v_addc_co_u32_e32 v35, vcc, 0, v21, vcc
	v_add_co_u32_e32 v36, vcc, 0x2e000, v20
	s_nop 1
	v_addc_co_u32_e32 v37, vcc, 0, v21, vcc
	global_load_dword v64, v[22:23], off nt
	global_load_dword v65, v[24:25], off nt
	global_load_dword v66, v[26:27], off nt
	global_load_dword v67, v[28:29], off nt
	global_load_dword v68, v[30:31], off nt
	global_load_dword v69, v[32:33], off nt
	global_load_dword v70, v[34:35], off nt
	s_nop 0
	global_load_dword v36, v[36:37], off nt
	v_add_co_u32_e32 v22, vcc, 0x30000, v20
	s_nop 1
	v_addc_co_u32_e32 v23, vcc, 0, v21, vcc
	v_add_co_u32_e32 v24, vcc, 0x32000, v20
	s_nop 1
	v_addc_co_u32_e32 v25, vcc, 0, v21, vcc
	v_add_co_u32_e32 v26, vcc, 0x34000, v20
	s_nop 1
	v_addc_co_u32_e32 v27, vcc, 0, v21, vcc
	v_add_co_u32_e32 v28, vcc, 0x36000, v20
	s_nop 1
	v_addc_co_u32_e32 v29, vcc, 0, v21, vcc
	v_add_co_u32_e32 v30, vcc, 0x38000, v20
	s_nop 1
	v_addc_co_u32_e32 v31, vcc, 0, v21, vcc
	v_add_co_u32_e32 v32, vcc, 0x3a000, v20
	s_nop 1
	v_addc_co_u32_e32 v33, vcc, 0, v21, vcc
	v_add_co_u32_e32 v34, vcc, 0x3c000, v20
	s_nop 1
	v_addc_co_u32_e32 v35, vcc, 0, v21, vcc
	v_add_co_u32_e32 v20, vcc, 0x3e000, v20
	s_nop 1
	v_addc_co_u32_e32 v21, vcc, 0, v21, vcc
	global_load_dword v22, v[22:23], off nt
	s_nop 0
	global_load_dword v23, v[24:25], off nt
	s_nop 0
	global_load_dword v24, v[26:27], off nt
	global_load_dword v25, v[28:29], off nt
	s_nop 0
	global_load_dword v26, v[30:31], off nt
	global_load_dword v27, v[32:33], off nt
	global_load_dword v28, v[34:35], off nt
	s_nop 0
	global_load_dword v20, v[20:21], off nt
	s_waitcnt vmcnt(30)
	ds_write2_b32 v53, v2, v38 offset1:66
	s_waitcnt vmcnt(28)
	ds_write2_b32 v53, v39, v40 offset0:132 offset1:198
	s_waitcnt vmcnt(26)
	ds_write2_b32 v56, v41, v42 offset0:8 offset1:74
	s_waitcnt vmcnt(24)
	ds_write2_b32 v56, v43, v44 offset0:140 offset1:206
	s_waitcnt vmcnt(22)
	ds_write2_b32 v57, v45, v46 offset0:16 offset1:82
	s_waitcnt vmcnt(20)
	ds_write2_b32 v57, v47, v48 offset0:148 offset1:214
	s_waitcnt vmcnt(18)
	ds_write2_b32 v58, v49, v50 offset0:24 offset1:90
	s_waitcnt vmcnt(16)
	ds_write2_b32 v58, v51, v63 offset0:156 offset1:222
	s_waitcnt vmcnt(14)
	ds_write2_b32 v59, v64, v65 offset0:32 offset1:98
	s_waitcnt vmcnt(12)
	ds_write2_b32 v59, v66, v67 offset0:164 offset1:230
	s_waitcnt vmcnt(10)
	ds_write2_b32 v60, v68, v69 offset0:40 offset1:106
	s_waitcnt vmcnt(8)
	ds_write2_b32 v60, v70, v36 offset0:172 offset1:238
	s_waitcnt vmcnt(6)
	ds_write2_b32 v61, v22, v23 offset0:48 offset1:114
	s_waitcnt vmcnt(4)
	ds_write2_b32 v61, v24, v25 offset0:180 offset1:246
	s_waitcnt vmcnt(2)
	ds_write2_b32 v62, v26, v27 offset0:56 offset1:122
	s_waitcnt vmcnt(0)
	ds_write2_b32 v62, v28, v20 offset0:188 offset1:254
	s_waitcnt lgkmcnt(0)
	ds_read2_b32 v[24:25], v54 offset0:33 offset1:41
	ds_read2_b32 v[26:27], v54 offset1:8
	ds_read2_b32 v[28:29], v54 offset0:66 offset1:74
	ds_read2_b32 v[30:31], v54 offset0:99 offset1:107
	ds_read2_b32 v[32:33], v54 offset0:132 offset1:140
	ds_read2_b32 v[34:35], v54 offset0:165 offset1:173
	ds_read2_b32 v[36:37], v54 offset0:198 offset1:206
	ds_read2_b32 v[38:39], v54 offset0:231 offset1:239
	v_or_b32_e32 v2, s0, v55
	s_lshl_b32 s0, s18, 1
	v_lshl_add_u64 v[40:41], v[6:7], 0, s[0:1]
	v_lshlrev_b32_e32 v2, 9, v2
	s_waitcnt lgkmcnt(6)
	v_cvt_pk_bf16_f32 v20, v26, v24
	s_waitcnt lgkmcnt(4)
	v_cvt_pk_bf16_f32 v21, v28, v30
	s_waitcnt lgkmcnt(2)
	v_cvt_pk_bf16_f32 v22, v32, v34
	s_waitcnt lgkmcnt(0)
	v_cvt_pk_bf16_f32 v23, v36, v38
	v_lshl_add_u64 v[40:41], v[40:41], 0, v[2:3]
	global_store_dwordx4 v[40:41], v[20:23], off sc1
	s_mov_b64 s[18:19], 0
	s_nop 0
	v_cvt_pk_bf16_f32 v20, v27, v25
	v_cvt_pk_bf16_f32 v21, v29, v31
	v_cvt_pk_bf16_f32 v22, v33, v35
	v_cvt_pk_bf16_f32 v23, v37, v39
	ds_read2_b32 v[24:25], v54 offset0:49 offset1:57
	ds_read2_b32 v[26:27], v54 offset0:16 offset1:24
	ds_read2_b32 v[28:29], v54 offset0:82 offset1:90
	ds_read2_b32 v[30:31], v54 offset0:115 offset1:123
	ds_read2_b32 v[32:33], v54 offset0:148 offset1:156
	ds_read2_b32 v[34:35], v54 offset0:181 offset1:189
	ds_read2_b32 v[36:37], v54 offset0:214 offset1:222
	ds_read2_b32 v[38:39], v54 offset0:247 offset1:255
	global_store_dwordx4 v[40:41], v[20:23], off offset:2048 sc1
	v_add_co_u32_e32 v40, vcc, s64, v40
	s_waitcnt lgkmcnt(6)
	v_cvt_pk_bf16_f32 v20, v26, v24
	s_waitcnt lgkmcnt(4)
	v_cvt_pk_bf16_f32 v21, v28, v30
	s_waitcnt lgkmcnt(2)
	v_cvt_pk_bf16_f32 v22, v32, v34
	s_waitcnt lgkmcnt(0)
	v_cvt_pk_bf16_f32 v23, v36, v38
	v_addc_co_u32_e32 v41, vcc, 0, v41, vcc
	global_store_dwordx4 v[40:41], v[20:23], off sc1
	s_nop 1
	v_cvt_pk_bf16_f32 v20, v27, v25
	v_cvt_pk_bf16_f32 v21, v29, v31
	v_cvt_pk_bf16_f32 v22, v33, v35
	v_cvt_pk_bf16_f32 v23, v37, v39
	global_store_dwordx4 v[40:41], v[20:23], off offset:2048 sc1
	s_waitcnt lgkmcnt(0)

.LBB0_29:
	s_waitcnt vmcnt(30)
	ds_write2_b32 v53, v20, v21 offset1:66
	s_waitcnt vmcnt(28)
	ds_write2_b32 v53, v22, v23 offset0:132 offset1:198
	s_waitcnt vmcnt(26)
	ds_write2_b32 v56, v24, v25 offset0:8 offset1:74
	s_waitcnt vmcnt(24)
	ds_write2_b32 v56, v26, v27 offset0:140 offset1:206
	s_waitcnt vmcnt(22)
	ds_write2_b32 v57, v28, v29 offset0:16 offset1:82
	s_waitcnt vmcnt(20)
	ds_write2_b32 v57, v30, v31 offset0:148 offset1:214
	s_waitcnt vmcnt(18)
	ds_write2_b32 v58, v32, v33 offset0:24 offset1:90
	s_waitcnt vmcnt(16)
	ds_write2_b32 v58, v34, v35 offset0:156 offset1:222
	s_waitcnt vmcnt(14)
	ds_write2_b32 v59, v36, v37 offset0:32 offset1:98
	s_waitcnt vmcnt(12)
	ds_write2_b32 v59, v38, v39 offset0:164 offset1:230
	s_waitcnt vmcnt(10)
	ds_write2_b32 v60, v40, v41 offset0:40 offset1:106
	s_waitcnt vmcnt(8)
	ds_write2_b32 v60, v42, v43 offset0:172 offset1:238
	s_waitcnt vmcnt(6)
	ds_write2_b32 v61, v44, v45 offset0:48 offset1:114
	s_waitcnt vmcnt(4)
	ds_write2_b32 v61, v46, v47 offset0:180 offset1:246
	s_waitcnt vmcnt(2)
	ds_write2_b32 v62, v50, v51 offset0:56 offset1:122
	s_waitcnt vmcnt(0)
	ds_write2_b32 v62, v48, v49 offset0:188 offset1:254
	s_waitcnt lgkmcnt(0)
	s_and_b32 s19, s46, 0x300
	s_and_b32 s44, s57, 0x80
	ds_read2_b32 v[24:25], v54 offset0:33 offset1:41
	ds_read2_b32 v[26:27], v54 offset1:8
	ds_read2_b32 v[28:29], v54 offset0:66 offset1:74
	ds_read2_b32 v[30:31], v54 offset0:99 offset1:107
	ds_read2_b32 v[32:33], v54 offset0:132 offset1:140
	ds_read2_b32 v[34:35], v54 offset0:165 offset1:173
	ds_read2_b32 v[36:37], v54 offset0:198 offset1:206
	ds_read2_b32 v[38:39], v54 offset0:231 offset1:239
	s_and_b32 s0, s50, 0x60
	s_or_b32 s19, s44, s19
	s_or_b32 s0, s19, s0
	v_or_b32_e32 v2, s0, v55
	s_lshl_b32 s0, s18, 1
	v_lshl_add_u64 v[40:41], v[10:11], 0, s[0:1]
	v_lshlrev_b32_e32 v2, 11, v2
	s_waitcnt lgkmcnt(6)
	v_cvt_pk_bf16_f32 v20, v26, v24
	s_waitcnt lgkmcnt(4)
	v_cvt_pk_bf16_f32 v21, v28, v30
	s_waitcnt lgkmcnt(2)
	v_cvt_pk_bf16_f32 v22, v32, v34
	s_waitcnt lgkmcnt(0)
	v_cvt_pk_bf16_f32 v23, v36, v38
	v_lshl_add_u64 v[40:41], v[40:41], 0, v[2:3]
	global_store_dwordx4 v[40:41], v[20:23], off sc1
	v_add_co_u32_e32 v24, vcc, s62, v40
	s_nop 0
	v_cvt_pk_bf16_f32 v20, v27, v25
	v_cvt_pk_bf16_f32 v21, v29, v31
	v_cvt_pk_bf16_f32 v22, v33, v35
	v_cvt_pk_bf16_f32 v23, v37, v39
	ds_read2_b32 v[26:27], v54 offset0:49 offset1:57
	ds_read2_b32 v[28:29], v54 offset0:16 offset1:24
	ds_read2_b32 v[30:31], v54 offset0:82 offset1:90
	ds_read2_b32 v[32:33], v54 offset0:115 offset1:123
	ds_read2_b32 v[34:35], v54 offset0:148 offset1:156
	ds_read2_b32 v[36:37], v54 offset0:181 offset1:189
	ds_read2_b32 v[38:39], v54 offset0:214 offset1:222
	ds_read2_b32 v[42:43], v54 offset0:247 offset1:255
	v_addc_co_u32_e32 v25, vcc, 0, v41, vcc
	global_store_dwordx4 v[24:25], v[20:23], off sc1
	v_add_co_u32_e32 v24, vcc, s63, v40
	s_waitcnt lgkmcnt(6)
	v_cvt_pk_bf16_f32 v20, v28, v26
	s_waitcnt lgkmcnt(4)
	v_cvt_pk_bf16_f32 v21, v30, v32
	s_waitcnt lgkmcnt(2)
	v_cvt_pk_bf16_f32 v22, v34, v36
	s_waitcnt lgkmcnt(0)
	v_cvt_pk_bf16_f32 v23, v38, v42
	v_addc_co_u32_e32 v25, vcc, 0, v41, vcc
	global_store_dwordx4 v[24:25], v[20:23], off sc1
	v_add_co_u32_e32 v24, vcc, 0x6000, v40
	s_nop 0
	v_cvt_pk_bf16_f32 v20, v29, v27
	v_cvt_pk_bf16_f32 v21, v31, v33
	v_cvt_pk_bf16_f32 v22, v35, v37
	v_cvt_pk_bf16_f32 v23, v39, v43
	v_addc_co_u32_e32 v25, vcc, 0, v41, vcc
	global_store_dwordx4 v[24:25], v[20:23], off sc1
	s_waitcnt lgkmcnt(0)

.LBB0_31:
	s_andn2_b64 vcc, exec, s[18:19]
	s_cbranch_vccnz .LBB0_33
	s_add_i32 s0, s60, 0x1f000
	s_and_b32 s18, s0, 0x1ffc0
	s_and_b32 s0, s46, 0x3e0
	v_or_b32_e32 v2, s18, v52
	s_lshl_b32 s0, s0, 2
	v_lshl_add_u64 v[20:21], v[12:13], 0, s[0:1]
	v_lshlrev_b32_e32 v2, 12, v2
	v_lshl_add_u64 v[20:21], v[20:21], 0, v[2:3]
	v_add_co_u32_e32 v22, vcc, 0x2000, v20
	s_and_b32 s19, s46, 0x300
	s_nop 0
	v_addc_co_u32_e32 v23, vcc, 0, v21, vcc
	v_add_co_u32_e32 v24, vcc, 0x4000, v20
	s_and_b32 s44, s57, 0x80
	s_nop 0
	v_addc_co_u32_e32 v25, vcc, 0, v21, vcc
	v_add_co_u32_e32 v26, vcc, 0x6000, v20
	s_and_b32 s0, s50, 0x60
	s_nop 0
	v_addc_co_u32_e32 v27, vcc, 0, v21, vcc
	v_add_co_u32_e32 v28, vcc, 0x8000, v20
	s_or_b32 s19, s44, s19
	s_nop 0
	v_addc_co_u32_e32 v29, vcc, 0, v21, vcc
	v_add_co_u32_e32 v30, vcc, 0xa000, v20
	s_or_b32 s0, s19, s0
	s_nop 0
	v_addc_co_u32_e32 v31, vcc, 0, v21, vcc
	v_add_co_u32_e32 v32, vcc, 0xc000, v20
	s_nop 1
	v_addc_co_u32_e32 v33, vcc, 0, v21, vcc
	v_add_co_u32_e32 v34, vcc, 0xe000, v20
	s_nop 1
	v_addc_co_u32_e32 v35, vcc, 0, v21, vcc
	global_load_dword v2, v[20:21], off nt
	global_load_dword v38, v[22:23], off nt
	global_load_dword v39, v[24:25], off nt
	global_load_dword v40, v[26:27], off nt
	global_load_dword v41, v[28:29], off nt
	global_load_dword v42, v[30:31], off nt
	global_load_dword v43, v[32:33], off nt
	global_load_dword v44, v[34:35], off nt
	v_add_co_u32_e32 v22, vcc, 0x10000, v20
	s_nop 1
	v_addc_co_u32_e32 v23, vcc, 0, v21, vcc
	v_add_co_u32_e32 v24, vcc, 0x12000, v20
	s_nop 1
	v_addc_co_u32_e32 v25, vcc, 0, v21, vcc
	v_add_co_u32_e32 v26, vcc, 0x14000, v20
	s_nop 1
	v_addc_co_u32_e32 v27, vcc, 0, v21, vcc
	v_add_co_u32_e32 v28, vcc, 0x16000, v20
	s_nop 1
	v_addc_co_u32_e32 v29, vcc, 0, v21, vcc
	v_add_co_u32_e32 v30, vcc, 0x18000, v20
	s_nop 1
	v_addc_co_u32_e32 v31, vcc, 0, v21, vcc
	v_add_co_u32_e32 v32, vcc, 0x1a000, v20
	s_nop 1
	v_addc_co_u32_e32 v33, vcc, 0, v21, vcc
	v_add_co_u32_e32 v34, vcc, 0x1c000, v20
	s_nop 1
	v_addc_co_u32_e32 v35, vcc, 0, v21, vcc
	v_add_co_u32_e32 v36, vcc, 0x1e000, v20
	s_nop 1
	v_addc_co_u32_e32 v37, vcc, 0, v21, vcc
	global_load_dword v45, v[22:23], off nt
	global_load_dword v46, v[24:25], off nt
	global_load_dword v47, v[26:27], off nt
	global_load_dword v48, v[28:29], off nt
	global_load_dword v49, v[30:31], off nt
	global_load_dword v50, v[32:33], off nt
	global_load_dword v51, v[34:35], off nt
	global_load_dword v63, v[36:37], off nt
	v_add_co_u32_e32 v22, vcc, 0x20000, v20
	s_nop 1
	v_addc_co_u32_e32 v23, vcc, 0, v21, vcc
	v_add_co_u32_e32 v24, vcc, 0x22000, v20
	s_nop 1
	v_addc_co_u32_e32 v25, vcc, 0, v21, vcc
	v_add_co_u32_e32 v26, vcc, 0x24000, v20
	s_nop 1
	v_addc_co_u32_e32 v27, vcc, 0, v21, vcc
	v_add_co_u32_e32 v28, vcc, 0x26000, v20
	s_nop 1
	v_addc_co_u32_e32 v29, vcc, 0, v21, vcc
	v_add_co_u32_e32 v30, vcc, 0x28000, v20
	s_nop 1
	v_addc_co_u32_e32 v31, vcc, 0, v21, vcc
	v_add_co_u32_e32 v32, vcc, 0x2a000, v20
	s_nop 1
	v_addc_co_u32_e32 v33, vcc, 0, v21, vcc
	v_add_co_u32_e32 v34, vcc, 0x2c000, v20
	s_nop 1
	v_addc_co_u32_e32 v35, vcc, 0, v21, vcc
	v_add_co_u32_e32 v36, vcc, 0x2e000, v20
	s_nop 1
	v_addc_co_u32_e32 v37, vcc, 0, v21, vcc
	global_load_dword v64, v[22:23], off nt
	global_load_dword v65, v[24:25], off nt
	global_load_dword v66, v[26:27], off nt
	global_load_dword v67, v[28:29], off nt
	global_load_dword v68, v[30:31], off nt
	global_load_dword v69, v[32:33], off nt
	global_load_dword v70, v[34:35], off nt
	s_nop 0
	global_load_dword v36, v[36:37], off nt
	v_add_co_u32_e32 v22, vcc, 0x30000, v20
	s_nop 1
	v_addc_co_u32_e32 v23, vcc, 0, v21, vcc
	v_add_co_u32_e32 v24, vcc, 0x32000, v20
	s_nop 1
	v_addc_co_u32_e32 v25, vcc, 0, v21, vcc
	v_add_co_u32_e32 v26, vcc, 0x34000, v20
	s_nop 1
	v_addc_co_u32_e32 v27, vcc, 0, v21, vcc
	v_add_co_u32_e32 v28, vcc, 0x36000, v20
	s_nop 1
	v_addc_co_u32_e32 v29, vcc, 0, v21, vcc
	v_add_co_u32_e32 v30, vcc, 0x38000, v20
	s_nop 1
	v_addc_co_u32_e32 v31, vcc, 0, v21, vcc
	v_add_co_u32_e32 v32, vcc, 0x3a000, v20
	s_nop 1
	v_addc_co_u32_e32 v33, vcc, 0, v21, vcc
	v_add_co_u32_e32 v34, vcc, 0x3c000, v20
	s_nop 1
	v_addc_co_u32_e32 v35, vcc, 0, v21, vcc
	v_add_co_u32_e32 v20, vcc, 0x3e000, v20
	s_nop 1
	v_addc_co_u32_e32 v21, vcc, 0, v21, vcc
	global_load_dword v22, v[22:23], off nt
	s_nop 0
	global_load_dword v23, v[24:25], off nt
	s_nop 0
	global_load_dword v24, v[26:27], off nt
	global_load_dword v25, v[28:29], off nt
	s_nop 0
	global_load_dword v26, v[30:31], off nt
	global_load_dword v27, v[32:33], off nt
	global_load_dword v28, v[34:35], off nt
	s_nop 0
	global_load_dword v20, v[20:21], off nt
	s_waitcnt vmcnt(30)
	ds_write2_b32 v53, v2, v38 offset1:66
	s_waitcnt vmcnt(28)
	ds_write2_b32 v53, v39, v40 offset0:132 offset1:198
	s_waitcnt vmcnt(26)
	ds_write2_b32 v56, v41, v42 offset0:8 offset1:74
	s_waitcnt vmcnt(24)
	ds_write2_b32 v56, v43, v44 offset0:140 offset1:206
	s_waitcnt vmcnt(22)
	ds_write2_b32 v57, v45, v46 offset0:16 offset1:82
	s_waitcnt vmcnt(20)
	ds_write2_b32 v57, v47, v48 offset0:148 offset1:214
	s_waitcnt vmcnt(18)
	ds_write2_b32 v58, v49, v50 offset0:24 offset1:90
	s_waitcnt vmcnt(16)
	ds_write2_b32 v58, v51, v63 offset0:156 offset1:222
	s_waitcnt vmcnt(14)
	ds_write2_b32 v59, v64, v65 offset0:32 offset1:98
	s_waitcnt vmcnt(12)
	ds_write2_b32 v59, v66, v67 offset0:164 offset1:230
	s_waitcnt vmcnt(10)
	ds_write2_b32 v60, v68, v69 offset0:40 offset1:106
	s_waitcnt vmcnt(8)
	ds_write2_b32 v60, v70, v36 offset0:172 offset1:238
	s_waitcnt vmcnt(6)
	ds_write2_b32 v61, v22, v23 offset0:48 offset1:114
	s_waitcnt vmcnt(4)
	ds_write2_b32 v61, v24, v25 offset0:180 offset1:246
	s_waitcnt vmcnt(2)
	ds_write2_b32 v62, v26, v27 offset0:56 offset1:122
	s_waitcnt vmcnt(0)
	ds_write2_b32 v62, v28, v20 offset0:188 offset1:254
	s_waitcnt lgkmcnt(0)
	ds_read2_b32 v[24:25], v54 offset0:33 offset1:41
	ds_read2_b32 v[26:27], v54 offset1:8
	ds_read2_b32 v[28:29], v54 offset0:66 offset1:74
	ds_read2_b32 v[30:31], v54 offset0:99 offset1:107
	ds_read2_b32 v[32:33], v54 offset0:132 offset1:140
	ds_read2_b32 v[34:35], v54 offset0:165 offset1:173
	ds_read2_b32 v[36:37], v54 offset0:198 offset1:206
	ds_read2_b32 v[38:39], v54 offset0:231 offset1:239
	v_or_b32_e32 v2, s0, v55
	s_lshl_b32 s0, s18, 1
	v_lshl_add_u64 v[40:41], v[14:15], 0, s[0:1]
	v_lshlrev_b32_e32 v2, 11, v2
	s_waitcnt lgkmcnt(6)
	v_cvt_pk_bf16_f32 v20, v26, v24
	s_waitcnt lgkmcnt(4)
	v_cvt_pk_bf16_f32 v21, v28, v30
	s_waitcnt lgkmcnt(2)
	v_cvt_pk_bf16_f32 v22, v32, v34
	s_waitcnt lgkmcnt(0)
	v_cvt_pk_bf16_f32 v23, v36, v38
	v_lshl_add_u64 v[40:41], v[40:41], 0, v[2:3]
	global_store_dwordx4 v[40:41], v[20:23], off sc1
	v_add_co_u32_e32 v24, vcc, s62, v40
	s_nop 0
	v_cvt_pk_bf16_f32 v20, v27, v25
	v_cvt_pk_bf16_f32 v21, v29, v31
	v_cvt_pk_bf16_f32 v22, v33, v35
	v_cvt_pk_bf16_f32 v23, v37, v39
	ds_read2_b32 v[26:27], v54 offset0:49 offset1:57
	ds_read2_b32 v[28:29], v54 offset0:16 offset1:24
	ds_read2_b32 v[30:31], v54 offset0:82 offset1:90
	ds_read2_b32 v[32:33], v54 offset0:115 offset1:123
	ds_read2_b32 v[34:35], v54 offset0:148 offset1:156
	ds_read2_b32 v[36:37], v54 offset0:181 offset1:189
	ds_read2_b32 v[38:39], v54 offset0:214 offset1:222
	ds_read2_b32 v[42:43], v54 offset0:247 offset1:255
	v_addc_co_u32_e32 v25, vcc, 0, v41, vcc
	global_store_dwordx4 v[24:25], v[20:23], off sc1
	v_add_co_u32_e32 v24, vcc, s63, v40
	s_waitcnt lgkmcnt(6)
	v_cvt_pk_bf16_f32 v20, v28, v26
	s_waitcnt lgkmcnt(4)
	v_cvt_pk_bf16_f32 v21, v30, v32
	s_waitcnt lgkmcnt(2)
	v_cvt_pk_bf16_f32 v22, v34, v36
	s_waitcnt lgkmcnt(0)
	v_cvt_pk_bf16_f32 v23, v38, v42
	v_addc_co_u32_e32 v25, vcc, 0, v41, vcc
	global_store_dwordx4 v[24:25], v[20:23], off sc1
	v_add_co_u32_e32 v24, vcc, 0x6000, v40
	s_nop 0
	v_cvt_pk_bf16_f32 v20, v29, v27
	v_cvt_pk_bf16_f32 v21, v31, v33
	v_cvt_pk_bf16_f32 v22, v35, v37
	v_cvt_pk_bf16_f32 v23, v39, v43
	v_addc_co_u32_e32 v25, vcc, 0, v41, vcc
	global_store_dwordx4 v[24:25], v[20:23], off sc1
	s_waitcnt lgkmcnt(0)

.LBB0_34:
	s_andn2_b64 vcc, exec, s[18:19]
	s_cbranch_vccnz .LBB0_21
	s_ashr_i32 s0, s65, 31
	s_lshr_b32 s0, s0, 25
	s_add_i32 s0, s65, s0
	s_ashr_i32 s0, s0, 7
	s_lshl_b32 s18, s0, 6
	s_lshl_b32 s0, s0, 12
	v_or_b32_e32 v20, s18, v52
	s_sub_i32 s44, s46, s0
	v_or_b32_e32 v26, 2, v20
	v_or_b32_e32 v28, 4, v20
	v_or_b32_e32 v30, 6, v20
	v_or_b32_e32 v32, 8, v20
	v_or_b32_e32 v34, 10, v20
	v_or_b32_e32 v36, 12, v20
	v_or_b32_e32 v38, 14, v20
	s_ashr_i32 s45, s44, 31
	v_ashrrev_i32_e32 v21, 31, v20
	v_ashrrev_i32_e32 v27, 31, v26
	v_ashrrev_i32_e32 v29, 31, v28
	v_ashrrev_i32_e32 v31, 31, v30
	v_ashrrev_i32_e32 v33, 31, v32
	v_ashrrev_i32_e32 v35, 31, v34
	v_ashrrev_i32_e32 v37, 31, v36
	v_ashrrev_i32_e32 v39, 31, v38
	v_lshl_add_u64 v[22:23], s[44:45], 2, v[16:17]
	v_lshlrev_b64 v[24:25], 14, v[20:21]
	v_lshlrev_b64 v[26:27], 14, v[26:27]
	v_lshlrev_b64 v[28:29], 14, v[28:29]
	v_lshlrev_b64 v[30:31], 14, v[30:31]
	v_lshlrev_b64 v[32:33], 14, v[32:33]
	v_lshlrev_b64 v[34:35], 14, v[34:35]
	v_lshlrev_b64 v[36:37], 14, v[36:37]
	v_lshlrev_b64 v[38:39], 14, v[38:39]
	v_lshl_add_u64 v[24:25], v[22:23], 0, v[24:25]
	v_lshl_add_u64 v[26:27], v[22:23], 0, v[26:27]
	v_lshl_add_u64 v[28:29], v[22:23], 0, v[28:29]
	v_lshl_add_u64 v[30:31], v[22:23], 0, v[30:31]
	v_lshl_add_u64 v[32:33], v[22:23], 0, v[32:33]
	v_lshl_add_u64 v[34:35], v[22:23], 0, v[34:35]
	v_lshl_add_u64 v[36:37], v[22:23], 0, v[36:37]
	v_lshl_add_u64 v[38:39], v[22:23], 0, v[38:39]
	global_load_dword v2, v[24:25], off nt
	global_load_dword v40, v[26:27], off nt
	global_load_dword v41, v[28:29], off nt
	global_load_dword v42, v[30:31], off nt
	global_load_dword v43, v[32:33], off nt
	global_load_dword v44, v[34:35], off nt
	global_load_dword v45, v[36:37], off nt
	global_load_dword v46, v[38:39], off nt
	v_or_b32_e32 v24, 16, v20
	v_or_b32_e32 v26, 18, v20
	v_or_b32_e32 v28, 20, v20
	v_or_b32_e32 v30, 22, v20
	v_or_b32_e32 v32, 24, v20
	v_or_b32_e32 v34, 26, v20
	v_or_b32_e32 v36, 28, v20
	v_or_b32_e32 v38, 30, v20
	v_ashrrev_i32_e32 v25, 31, v24
	v_ashrrev_i32_e32 v27, 31, v26
	v_ashrrev_i32_e32 v29, 31, v28
	v_ashrrev_i32_e32 v31, 31, v30
	v_ashrrev_i32_e32 v33, 31, v32
	v_ashrrev_i32_e32 v35, 31, v34
	v_ashrrev_i32_e32 v37, 31, v36
	v_ashrrev_i32_e32 v39, 31, v38
	v_lshlrev_b64 v[24:25], 14, v[24:25]
	v_lshlrev_b64 v[26:27], 14, v[26:27]
	v_lshlrev_b64 v[28:29], 14, v[28:29]
	v_lshlrev_b64 v[30:31], 14, v[30:31]
	v_lshlrev_b64 v[32:33], 14, v[32:33]
	v_lshlrev_b64 v[34:35], 14, v[34:35]
	v_lshlrev_b64 v[36:37], 14, v[36:37]
	v_lshlrev_b64 v[38:39], 14, v[38:39]
	v_lshl_add_u64 v[24:25], v[22:23], 0, v[24:25]
	v_lshl_add_u64 v[26:27], v[22:23], 0, v[26:27]
	v_lshl_add_u64 v[28:29], v[22:23], 0, v[28:29]
	v_lshl_add_u64 v[30:31], v[22:23], 0, v[30:31]
	v_lshl_add_u64 v[32:33], v[22:23], 0, v[32:33]
	v_lshl_add_u64 v[34:35], v[22:23], 0, v[34:35]
	v_lshl_add_u64 v[36:37], v[22:23], 0, v[36:37]
	v_lshl_add_u64 v[38:39], v[22:23], 0, v[38:39]
	global_load_dword v47, v[24:25], off nt
	global_load_dword v48, v[26:27], off nt
	global_load_dword v49, v[28:29], off nt
	global_load_dword v50, v[30:31], off nt
	global_load_dword v51, v[32:33], off nt
	global_load_dword v63, v[34:35], off nt
	global_load_dword v64, v[36:37], off nt
	global_load_dword v65, v[38:39], off nt
	v_or_b32_e32 v24, 32, v20
	v_or_b32_e32 v26, 34, v20
	v_or_b32_e32 v28, 36, v20
	v_or_b32_e32 v30, 38, v20
	v_or_b32_e32 v32, 40, v20
	v_or_b32_e32 v34, 42, v20
	v_or_b32_e32 v36, 44, v20
	v_or_b32_e32 v38, 46, v20
	v_ashrrev_i32_e32 v25, 31, v24
	v_ashrrev_i32_e32 v27, 31, v26
	v_ashrrev_i32_e32 v29, 31, v28
	v_ashrrev_i32_e32 v31, 31, v30
	v_ashrrev_i32_e32 v33, 31, v32
	v_ashrrev_i32_e32 v35, 31, v34
	v_ashrrev_i32_e32 v37, 31, v36
	v_ashrrev_i32_e32 v39, 31, v38
	v_lshlrev_b64 v[24:25], 14, v[24:25]
	v_lshlrev_b64 v[26:27], 14, v[26:27]
	v_lshlrev_b64 v[28:29], 14, v[28:29]
	v_lshlrev_b64 v[30:31], 14, v[30:31]
	v_lshlrev_b64 v[32:33], 14, v[32:33]
	v_lshlrev_b64 v[34:35], 14, v[34:35]
	v_lshlrev_b64 v[36:37], 14, v[36:37]
	v_lshlrev_b64 v[38:39], 14, v[38:39]
	v_lshl_add_u64 v[24:25], v[22:23], 0, v[24:25]
	v_lshl_add_u64 v[26:27], v[22:23], 0, v[26:27]
	v_lshl_add_u64 v[28:29], v[22:23], 0, v[28:29]
	v_lshl_add_u64 v[30:31], v[22:23], 0, v[30:31]
	v_lshl_add_u64 v[32:33], v[22:23], 0, v[32:33]
	v_lshl_add_u64 v[34:35], v[22:23], 0, v[34:35]
	v_lshl_add_u64 v[36:37], v[22:23], 0, v[36:37]
	v_lshl_add_u64 v[38:39], v[22:23], 0, v[38:39]
	global_load_dword v66, v[24:25], off nt
	global_load_dword v67, v[26:27], off nt
	global_load_dword v68, v[28:29], off nt
	global_load_dword v69, v[30:31], off nt
	global_load_dword v70, v[32:33], off nt
	global_load_dword v71, v[34:35], off nt
	global_load_dword v72, v[36:37], off nt
	s_nop 0
	global_load_dword v38, v[38:39], off nt
	v_or_b32_e32 v24, 48, v20
	v_or_b32_e32 v26, 50, v20
	v_or_b32_e32 v28, 52, v20
	v_or_b32_e32 v30, 54, v20
	v_or_b32_e32 v32, 56, v20
	v_or_b32_e32 v34, 58, v20
	v_or_b32_e32 v36, 60, v20
	v_or_b32_e32 v20, 62, v20
	v_ashrrev_i32_e32 v25, 31, v24
	v_ashrrev_i32_e32 v27, 31, v26
	v_ashrrev_i32_e32 v29, 31, v28
	v_ashrrev_i32_e32 v21, 31, v20
	v_lshlrev_b64 v[24:25], 14, v[24:25]
	v_lshlrev_b64 v[26:27], 14, v[26:27]
	v_lshlrev_b64 v[28:29], 14, v[28:29]
	v_ashrrev_i32_e32 v31, 31, v30
	v_ashrrev_i32_e32 v33, 31, v32
	v_ashrrev_i32_e32 v35, 31, v34
	v_ashrrev_i32_e32 v37, 31, v36
	v_lshlrev_b64 v[20:21], 14, v[20:21]
	v_lshl_add_u64 v[24:25], v[22:23], 0, v[24:25]
	v_lshl_add_u64 v[26:27], v[22:23], 0, v[26:27]
	v_lshl_add_u64 v[28:29], v[22:23], 0, v[28:29]
	v_lshlrev_b64 v[30:31], 14, v[30:31]
	v_lshlrev_b64 v[32:33], 14, v[32:33]
	v_lshlrev_b64 v[34:35], 14, v[34:35]
	v_lshlrev_b64 v[36:37], 14, v[36:37]
	v_lshl_add_u64 v[20:21], v[22:23], 0, v[20:21]
	v_lshl_add_u64 v[30:31], v[22:23], 0, v[30:31]
	v_lshl_add_u64 v[32:33], v[22:23], 0, v[32:33]
	v_lshl_add_u64 v[34:35], v[22:23], 0, v[34:35]
	v_lshl_add_u64 v[36:37], v[22:23], 0, v[36:37]
	global_load_dword v22, v[24:25], off nt
	global_load_dword v23, v[26:27], off nt
	s_nop 0
	global_load_dword v24, v[28:29], off nt
	global_load_dword v25, v[30:31], off nt
	global_load_dword v26, v[32:33], off nt
	global_load_dword v27, v[34:35], off nt
	s_nop 0
	global_load_dword v28, v[36:37], off nt
	s_nop 0
	global_load_dword v20, v[20:21], off nt
	s_waitcnt vmcnt(30)
	ds_write2_b32 v53, v2, v40 offset1:66
	s_waitcnt vmcnt(28)
	ds_write2_b32 v53, v41, v42 offset0:132 offset1:198
	s_waitcnt vmcnt(26)
	ds_write2_b32 v56, v43, v44 offset0:8 offset1:74
	s_waitcnt vmcnt(24)
	ds_write2_b32 v56, v45, v46 offset0:140 offset1:206
	s_waitcnt vmcnt(22)
	ds_write2_b32 v57, v47, v48 offset0:16 offset1:82
	s_waitcnt vmcnt(20)
	ds_write2_b32 v57, v49, v50 offset0:148 offset1:214
	s_waitcnt vmcnt(18)
	ds_write2_b32 v58, v51, v63 offset0:24 offset1:90
	s_waitcnt vmcnt(16)
	ds_write2_b32 v58, v64, v65 offset0:156 offset1:222
	s_waitcnt vmcnt(14)
	ds_write2_b32 v59, v66, v67 offset0:32 offset1:98
	s_waitcnt vmcnt(12)
	ds_write2_b32 v59, v68, v69 offset0:164 offset1:230
	s_waitcnt vmcnt(10)
	ds_write2_b32 v60, v70, v71 offset0:40 offset1:106
	s_waitcnt vmcnt(8)
	ds_write2_b32 v60, v72, v38 offset0:172 offset1:238
	s_waitcnt vmcnt(6)
	ds_write2_b32 v61, v22, v23 offset0:48 offset1:114
	s_waitcnt vmcnt(4)
	ds_write2_b32 v61, v24, v25 offset0:180 offset1:246
	s_waitcnt vmcnt(2)
	ds_write2_b32 v62, v26, v27 offset0:56 offset1:122
	s_waitcnt vmcnt(0)
	ds_write2_b32 v62, v28, v20 offset0:188 offset1:254
	s_and_b32 s19, s44, 0xffffff00
	s_and_b32 s44, s57, 0x80
	s_waitcnt lgkmcnt(0)
	s_and_b32 s0, s50, 0x60
	s_or_b32 s19, s44, s19
	ds_read2_b32 v[26:27], v54 offset0:33 offset1:41
	ds_read2_b32 v[28:29], v54 offset1:8
	ds_read2_b32 v[30:31], v54 offset0:66 offset1:74
	ds_read2_b32 v[32:33], v54 offset0:99 offset1:107
	ds_read2_b32 v[34:35], v54 offset0:132 offset1:140
	ds_read2_b32 v[36:37], v54 offset0:165 offset1:173
	ds_read2_b32 v[38:39], v54 offset0:198 offset1:206
	ds_read2_b32 v[40:41], v54 offset0:231 offset1:239
	s_or_b32 s0, s19, s0
	v_or_b32_e32 v24, s0, v55
	s_ashr_i32 s19, s18, 31
	v_ashrrev_i32_e32 v25, 31, v24
	v_lshl_add_u64 v[42:43], s[18:19], 1, v[18:19]
	v_lshlrev_b64 v[44:45], 11, v[24:25]
	s_waitcnt lgkmcnt(6)
	v_cvt_pk_bf16_f32 v20, v28, v26
	s_waitcnt lgkmcnt(4)
	v_cvt_pk_bf16_f32 v21, v30, v32
	s_waitcnt lgkmcnt(2)
	v_cvt_pk_bf16_f32 v22, v34, v36
	s_waitcnt lgkmcnt(0)
	v_cvt_pk_bf16_f32 v23, v38, v40
	v_lshl_add_u64 v[44:45], v[42:43], 0, v[44:45]
	v_or_b32_e32 v26, 4, v24
	global_store_dwordx4 v[44:45], v[20:23], off sc1
	s_nop 1
	v_cvt_pk_bf16_f32 v20, v29, v27
	v_ashrrev_i32_e32 v27, 31, v26
	v_cvt_pk_bf16_f32 v21, v31, v33
	v_cvt_pk_bf16_f32 v22, v35, v37
	v_cvt_pk_bf16_f32 v23, v39, v41
	v_lshlrev_b64 v[26:27], 11, v[26:27]
	ds_read2_b32 v[28:29], v54 offset0:49 offset1:57
	ds_read2_b32 v[30:31], v54 offset0:16 offset1:24
	ds_read2_b32 v[32:33], v54 offset0:82 offset1:90
	ds_read2_b32 v[34:35], v54 offset0:115 offset1:123
	ds_read2_b32 v[36:37], v54 offset0:148 offset1:156
	ds_read2_b32 v[38:39], v54 offset0:181 offset1:189
	ds_read2_b32 v[40:41], v54 offset0:214 offset1:222
	ds_read2_b32 v[44:45], v54 offset0:247 offset1:255
	v_lshl_add_u64 v[26:27], v[42:43], 0, v[26:27]
	global_store_dwordx4 v[26:27], v[20:23], off sc1
	v_or_b32_e32 v26, 8, v24
	v_ashrrev_i32_e32 v27, 31, v26
	v_or_b32_e32 v24, 12, v24
	v_lshlrev_b64 v[26:27], 11, v[26:27]
	v_ashrrev_i32_e32 v25, 31, v24
	s_waitcnt lgkmcnt(6)
	v_cvt_pk_bf16_f32 v20, v30, v28
	s_waitcnt lgkmcnt(4)
	v_cvt_pk_bf16_f32 v21, v32, v34
	s_waitcnt lgkmcnt(2)
	v_cvt_pk_bf16_f32 v22, v36, v38
	s_waitcnt lgkmcnt(0)
	v_cvt_pk_bf16_f32 v23, v40, v44
	v_lshl_add_u64 v[26:27], v[42:43], 0, v[26:27]
	v_lshlrev_b64 v[24:25], 11, v[24:25]
	global_store_dwordx4 v[26:27], v[20:23], off sc1
	v_lshl_add_u64 v[24:25], v[42:43], 0, v[24:25]
	s_nop 0
	v_cvt_pk_bf16_f32 v20, v31, v29
	v_cvt_pk_bf16_f32 v21, v33, v35
	v_cvt_pk_bf16_f32 v22, v37, v39
	v_cvt_pk_bf16_f32 v23, v41, v45
	global_store_dwordx4 v[24:25], v[20:23], off sc1
	s_waitcnt lgkmcnt(0)
	s_branch .LBB0_21

.LBB0_71:
	s_andn2_saveexec_b64 s[16:17], s[16:17]
	s_cbranch_execz .LBB0_91
	s_mov_b64 s[16:17], exec
	s_nop 0
	s_waitcnt lgkmcnt(0)
	s_waitcnt vmcnt(0)
	v_mbcnt_lo_u32_b32 v1, s16, 0
	v_mbcnt_hi_u32_b32 v1, s17, v1
	v_cmp_eq_u32_e32 vcc, 0, v1
	s_and_saveexec_b64 s[28:29], vcc
	s_cbranch_execz .LBB0_74
	s_bcnt1_i32_b64 s16, s[16:17]
	v_mov_b32_e32 v2, 0x4000
	v_mov_b32_e32 v3, s16
	global_atomic_add v2, v2, v3, s[52:53] offset:1024 sc0

.LBB0_223:
	s_andn2_saveexec_b64 s[6:7], s[6:7]
	s_cbranch_execz .LBB0_243
	s_mov_b64 s[6:7], exec
	s_nop 0
	s_waitcnt lgkmcnt(0)
	s_waitcnt vmcnt(0)
	v_mbcnt_lo_u32_b32 v1, s6, 0
	v_mbcnt_hi_u32_b32 v1, s7, v1
	v_cmp_eq_u32_e32 vcc, 0, v1
	s_and_saveexec_b64 s[16:17], vcc
	s_cbranch_execz .LBB0_226
	s_bcnt1_i32_b64 s6, s[6:7]
	v_mov_b32_e32 v2, 0x4000
	v_mov_b32_e32 v3, s6
	global_atomic_add v2, v2, v3, s[52:53] offset:1024 sc0

.LBB0_265:
	s_cmpk_gt_u32 s36, 0xff
	s_waitcnt lgkmcnt(0)
	s_barrier
	s_cbranch_scc1 .LBB0_267
	ds_read2st64_b32 v[78:79], v64 offset1:1
	ds_read2st64_b32 v[80:81], v64 offset0:2 offset1:3
	ds_read2st64_b32 v[82:83], v64 offset0:4 offset1:5
	ds_read2st64_b32 v[84:85], v64 offset0:6 offset1:7
	ds_read2st64_b32 v[86:87], v64 offset0:8 offset1:9
	ds_read2st64_b32 v[126:127], v64 offset0:10 offset1:11
	ds_read2st64_b32 v[128:129], v64 offset0:12 offset1:13
	ds_read2st64_b32 v[132:133], v64 offset0:14 offset1:15
	ds_read2st64_b32 v[134:135], v64 offset0:16 offset1:17
	ds_read2st64_b32 v[136:137], v64 offset0:18 offset1:19
	ds_read2st64_b32 v[138:139], v64 offset0:20 offset1:21
	ds_read2st64_b32 v[140:141], v64 offset0:22 offset1:23
	ds_read2st64_b32 v[142:143], v64 offset0:24 offset1:25
	ds_read2st64_b32 v[144:145], v64 offset0:26 offset1:27
	ds_read2st64_b32 v[124:125], v64 offset0:28 offset1:29
	ds_read2st64_b32 v[146:147], v64 offset0:30 offset1:31
	ds_read2st64_b32 v[116:117], v64 offset0:32 offset1:33
	ds_read2st64_b32 v[120:121], v64 offset0:34 offset1:35
	ds_read2st64_b32 v[106:107], v64 offset0:36 offset1:37
	ds_read2st64_b32 v[114:115], v64 offset0:38 offset1:39
	ds_read2st64_b32 v[94:95], v64 offset0:40 offset1:41
	ds_read2st64_b32 v[100:101], v64 offset0:42 offset1:43
	ds_read2st64_b32 v[92:93], v64 offset0:44 offset1:45
	ds_read2st64_b32 v[96:97], v64 offset0:46 offset1:47
	ds_read2st64_b32 v[88:89], v64 offset0:56 offset1:57
	ds_read2st64_b32 v[90:91], v64 offset0:58 offset1:59
	ds_read2st64_b32 v[66:67], v64 offset0:60 offset1:61
	ds_read2st64_b32 v[68:69], v64 offset0:62 offset1:63
	ds_read2st64_b32 v[104:105], v64 offset0:48 offset1:49
	ds_read2st64_b32 v[110:111], v64 offset0:50 offset1:51
	ds_read2st64_b32 v[98:99], v64 offset0:52 offset1:53
	ds_read2st64_b32 v[102:103], v64 offset0:54 offset1:55
	s_waitcnt lgkmcnt(14)
	v_pk_mul_f32 v[78:79], v[180:181], v[78:79]
	v_pk_mul_f32 v[80:81], v[180:181], v[80:81]
	v_pk_fma_f32 v[48:49], v[48:49], v[70:71], v[78:79] op_sel_hi:[1,0,1] neg_lo:[0,0,1] neg_hi:[0,0,1]
	v_pk_mul_f32 v[78:79], v[180:181], v[84:85]
	v_pk_fma_f32 v[50:51], v[50:51], v[70:71], v[80:81] op_sel_hi:[1,0,1] neg_lo:[0,0,1] neg_hi:[0,0,1]
	v_pk_fma_f32 v[54:55], v[54:55], v[70:71], v[78:79] op_sel_hi:[1,0,1] neg_lo:[0,0,1] neg_hi:[0,0,1]
	v_pk_mul_f32 v[78:79], v[180:181], v[82:83]
	s_waitcnt lgkmcnt(5)
	v_pk_mul_f32 v[64:65], v[180:181], v[66:67]
	v_pk_fma_f32 v[78:79], v[52:53], v[70:71], v[78:79] op_sel_hi:[1,0,1] neg_lo:[0,0,1] neg_hi:[0,0,1]
	v_pk_mul_f32 v[52:53], v[180:181], v[126:127]
	v_pk_fma_f32 v[64:65], v[12:13], v[70:71], v[64:65] op_sel_hi:[1,0,1] neg_lo:[0,0,1] neg_hi:[0,0,1]
	v_pk_fma_f32 v[52:53], v[58:59], v[70:71], v[52:53] op_sel_hi:[1,0,1] neg_lo:[0,0,1] neg_hi:[0,0,1]
	v_pk_mul_f32 v[58:59], v[180:181], v[86:87]
	s_waitcnt lgkmcnt(4)
	v_pk_mul_f32 v[12:13], v[180:181], v[68:69]
	v_pk_fma_f32 v[80:81], v[56:57], v[70:71], v[58:59] op_sel_hi:[1,0,1] neg_lo:[0,0,1] neg_hi:[0,0,1]
	v_pk_mul_f32 v[56:57], v[180:181], v[132:133]
	v_pk_fma_f32 v[66:67], v[14:15], v[70:71], v[12:13] op_sel_hi:[1,0,1] neg_lo:[0,0,1] neg_hi:[0,0,1]
	v_pk_fma_f32 v[62:63], v[62:63], v[70:71], v[56:57] op_sel_hi:[1,0,1] neg_lo:[0,0,1] neg_hi:[0,0,1]
	v_pk_mul_f32 v[56:57], v[180:181], v[128:129]
	v_lshlrev_b32_e32 v12, 10, v159
	v_pk_fma_f32 v[84:85], v[60:61], v[70:71], v[56:57] op_sel_hi:[1,0,1] neg_lo:[0,0,1] neg_hi:[0,0,1]
	v_pk_mul_f32 v[56:57], v[180:181], v[136:137]
	v_lshl_or_b32 v12, s26, 7, v12
	v_pk_fma_f32 v[56:57], v[34:35], v[70:71], v[56:57] op_sel_hi:[1,0,1] neg_lo:[0,0,1] neg_hi:[0,0,1]
	v_pk_mul_f32 v[34:35], v[180:181], v[134:135]
	v_or_b32_e32 v68, s27, v12
	v_pk_fma_f32 v[60:61], v[32:33], v[70:71], v[34:35] op_sel_hi:[1,0,1] neg_lo:[0,0,1] neg_hi:[0,0,1]
	v_pk_mul_f32 v[32:33], v[180:181], v[140:141]
	v_lshlrev_b32_e32 v130, 1, v68
	v_pk_fma_f32 v[58:59], v[38:39], v[70:71], v[32:33] op_sel_hi:[1,0,1] neg_lo:[0,0,1] neg_hi:[0,0,1]
	v_pk_mul_f32 v[32:33], v[180:181], v[138:139]
	v_lshl_add_u64 v[68:69], s[16:17], 0, v[130:131]
	v_pk_fma_f32 v[82:83], v[36:37], v[70:71], v[32:33] op_sel_hi:[1,0,1] neg_lo:[0,0,1] neg_hi:[0,0,1]
	v_pk_mul_f32 v[32:33], v[180:181], v[144:145]
	v_mov_b32_e32 v159, v131
	v_pk_fma_f32 v[42:43], v[42:43], v[70:71], v[32:33] op_sel_hi:[1,0,1] neg_lo:[0,0,1] neg_hi:[0,0,1]
	v_pk_mul_f32 v[32:33], v[180:181], v[142:143]
	v_pk_mul_f32 v[112:113], v[48:49], v[48:49]
	v_pk_fma_f32 v[86:87], v[40:41], v[70:71], v[32:33] op_sel_hi:[1,0,1] neg_lo:[0,0,1] neg_hi:[0,0,1]
	v_pk_mul_f32 v[32:33], v[180:181], v[146:147]
	global_load_dwordx4 v[12:15], v156, s[40:41]
	v_pk_fma_f32 v[40:41], v[46:47], v[70:71], v[32:33] op_sel_hi:[1,0,1] neg_lo:[0,0,1] neg_hi:[0,0,1]
	v_pk_mul_f32 v[32:33], v[180:181], v[124:125]
	v_lshl_add_u64 v[68:69], v[68:69], 0, v[158:159]
	v_pk_fma_f32 v[44:45], v[44:45], v[70:71], v[32:33] op_sel_hi:[1,0,1] neg_lo:[0,0,1] neg_hi:[0,0,1]
	v_pk_mul_f32 v[32:33], v[180:181], v[120:121]
	v_pk_mul_f32 v[108:109], v[50:51], v[50:51]
	v_pk_fma_f32 v[32:33], v[18:19], v[70:71], v[32:33] op_sel_hi:[1,0,1] neg_lo:[0,0,1] neg_hi:[0,0,1]
	v_pk_mul_f32 v[18:19], v[180:181], v[116:117]
	global_load_dwordx2 v[74:75], v[68:69], off
	v_pk_fma_f32 v[34:35], v[16:17], v[70:71], v[18:19] op_sel_hi:[1,0,1] neg_lo:[0,0,1] neg_hi:[0,0,1]
	v_pk_mul_f32 v[16:17], v[180:181], v[114:115]
	v_pk_mul_f32 v[122:123], v[78:79], v[78:79]
	v_pk_fma_f32 v[36:37], v[22:23], v[70:71], v[16:17] op_sel_hi:[1,0,1] neg_lo:[0,0,1] neg_hi:[0,0,1]
	v_pk_mul_f32 v[16:17], v[180:181], v[106:107]
	v_pk_mul_f32 v[118:119], v[54:55], v[54:55]
	v_pk_fma_f32 v[38:39], v[20:21], v[70:71], v[16:17] op_sel_hi:[1,0,1] neg_lo:[0,0,1] neg_hi:[0,0,1]
	v_pk_mul_f32 v[16:17], v[180:181], v[100:101]
	v_pk_mul_f32 v[148:149], v[80:81], v[80:81]
	v_pk_fma_f32 v[26:27], v[26:27], v[70:71], v[16:17] op_sel_hi:[1,0,1] neg_lo:[0,0,1] neg_hi:[0,0,1]
	v_pk_mul_f32 v[16:17], v[180:181], v[94:95]
	v_pk_mul_f32 v[126:127], v[52:53], v[52:53]
	v_pk_fma_f32 v[24:25], v[24:25], v[70:71], v[16:17] op_sel_hi:[1,0,1] neg_lo:[0,0,1] neg_hi:[0,0,1]
	v_pk_mul_f32 v[16:17], v[180:181], v[96:97]
	v_pk_mul_f32 v[128:129], v[84:85], v[84:85]
	v_pk_fma_f32 v[20:21], v[30:31], v[70:71], v[16:17] op_sel_hi:[1,0,1] neg_lo:[0,0,1] neg_hi:[0,0,1]
	v_pk_mul_f32 v[16:17], v[180:181], v[92:93]
	v_pk_mul_f32 v[132:133], v[62:63], v[62:63]
	v_pk_fma_f32 v[22:23], v[28:29], v[70:71], v[16:17] op_sel_hi:[1,0,1] neg_lo:[0,0,1] neg_hi:[0,0,1]
	s_waitcnt lgkmcnt(2)
	v_pk_mul_f32 v[16:17], v[180:181], v[110:111]
	v_pk_mul_f32 v[134:135], v[60:61], v[60:61]
	v_pk_fma_f32 v[16:17], v[2:3], v[70:71], v[16:17] op_sel_hi:[1,0,1] neg_lo:[0,0,1] neg_hi:[0,0,1]
	v_pk_mul_f32 v[2:3], v[180:181], v[104:105]
	v_pk_mul_f32 v[136:137], v[56:57], v[56:57]
	v_pk_fma_f32 v[18:19], v[0:1], v[70:71], v[2:3] op_sel_hi:[1,0,1] neg_lo:[0,0,1] neg_hi:[0,0,1]
	s_waitcnt lgkmcnt(0)
	v_pk_mul_f32 v[0:1], v[180:181], v[102:103]
	v_pk_mul_f32 v[2:3], v[180:181], v[98:99]
	v_pk_fma_f32 v[0:1], v[6:7], v[70:71], v[0:1] op_sel_hi:[1,0,1] neg_lo:[0,0,1] neg_hi:[0,0,1]
	v_pk_fma_f32 v[4:5], v[4:5], v[70:71], v[2:3] op_sel_hi:[1,0,1] neg_lo:[0,0,1] neg_hi:[0,0,1]
	v_pk_mul_f32 v[2:3], v[180:181], v[90:91]
	v_pk_mul_f32 v[6:7], v[180:181], v[88:89]
	v_pk_fma_f32 v[2:3], v[10:11], v[70:71], v[2:3] op_sel_hi:[1,0,1] neg_lo:[0,0,1] neg_hi:[0,0,1]
	v_pk_fma_f32 v[6:7], v[8:9], v[70:71], v[6:7] op_sel_hi:[1,0,1] neg_lo:[0,0,1] neg_hi:[0,0,1]
	v_add_f32_e32 v70, v112, v113
	v_add_f32_e32 v70, v70, v108
	v_add_f32_e32 v70, v70, v109
	v_add_f32_e32 v70, v70, v122
	v_add_f32_e32 v70, v70, v123
	v_add_f32_e32 v70, v70, v118
	v_add_f32_e32 v70, v70, v119
	v_add_f32_e32 v70, v70, v148
	v_add_f32_e32 v70, v70, v149
	v_add_f32_e32 v70, v70, v126
	v_add_f32_e32 v70, v70, v127
	v_add_f32_e32 v70, v70, v128
	v_add_f32_e32 v70, v70, v129
	v_add_f32_e32 v70, v70, v132
	v_add_f32_e32 v70, v70, v133
	v_add_f32_e32 v70, v70, v134
	v_add_f32_e32 v70, v70, v135
	v_add_f32_e32 v70, v70, v136
	v_pk_mul_f32 v[138:139], v[82:83], v[82:83]
	v_add_f32_e32 v70, v70, v137
	v_add_f32_e32 v70, v70, v138
	v_pk_mul_f32 v[140:141], v[58:59], v[58:59]
	v_add_f32_e32 v70, v70, v139
	v_add_f32_e32 v70, v70, v140
	v_pk_mul_f32 v[142:143], v[86:87], v[86:87]
	v_add_f32_e32 v70, v70, v141
	v_add_f32_e32 v70, v70, v142
	v_pk_mul_f32 v[144:145], v[42:43], v[42:43]
	v_add_f32_e32 v70, v70, v143
	v_add_f32_e32 v70, v70, v144
	v_pk_mul_f32 v[124:125], v[44:45], v[44:45]
	v_add_f32_e32 v70, v70, v145
	v_add_f32_e32 v70, v70, v124
	v_pk_mul_f32 v[46:47], v[40:41], v[40:41]
	v_add_f32_e32 v70, v70, v125
	v_add_f32_e32 v46, v70, v46
	v_pk_mul_f32 v[116:117], v[34:35], v[34:35]
	v_add_f32_e32 v46, v46, v47
	v_add_f32_e32 v46, v46, v116
	v_pk_mul_f32 v[120:121], v[32:33], v[32:33]
	v_add_f32_e32 v46, v46, v117
	v_add_f32_e32 v46, v46, v120
	v_pk_mul_f32 v[106:107], v[38:39], v[38:39]
	v_add_f32_e32 v46, v46, v121
	v_add_f32_e32 v46, v46, v106
	v_pk_mul_f32 v[114:115], v[36:37], v[36:37]
	v_add_f32_e32 v46, v46, v107
	v_add_f32_e32 v46, v46, v114
	v_pk_mul_f32 v[94:95], v[24:25], v[24:25]
	v_add_f32_e32 v46, v46, v115
	v_add_f32_e32 v46, v46, v94
	v_pk_mul_f32 v[100:101], v[26:27], v[26:27]
	v_add_f32_e32 v46, v46, v95
	v_add_f32_e32 v46, v46, v100
	v_pk_mul_f32 v[28:29], v[22:23], v[22:23]
	v_add_f32_e32 v46, v46, v101
	v_add_f32_e32 v28, v46, v28
	v_pk_mul_f32 v[30:31], v[20:21], v[20:21]
	v_add_f32_e32 v28, v28, v29
	v_add_f32_e32 v28, v28, v30
	v_pk_mul_f32 v[96:97], v[18:19], v[18:19]
	v_add_f32_e32 v28, v28, v31
	v_add_f32_e32 v28, v28, v96
	v_pk_mul_f32 v[92:93], v[16:17], v[16:17]
	v_add_f32_e32 v28, v28, v97
	v_add_f32_e32 v28, v28, v92
	v_pk_mul_f32 v[98:99], v[4:5], v[4:5]
	v_add_f32_e32 v28, v28, v93
	v_add_f32_e32 v28, v28, v98
	v_pk_mul_f32 v[102:103], v[0:1], v[0:1]
	v_add_f32_e32 v28, v28, v99
	v_add_f32_e32 v28, v28, v102
	v_pk_mul_f32 v[8:9], v[6:7], v[6:7]
	v_add_f32_e32 v28, v28, v103
	v_add_f32_e32 v8, v28, v8
	v_pk_mul_f32 v[10:11], v[2:3], v[2:3]
	v_add_f32_e32 v8, v8, v9
	v_add_f32_e32 v8, v8, v10
	v_pk_mul_f32 v[72:73], v[64:65], v[64:65]
	v_add_f32_e32 v8, v8, v11
	v_add_f32_e32 v8, v8, v72
	v_pk_mul_f32 v[76:77], v[66:67], v[66:67]
	v_add_f32_e32 v8, v8, v73
	v_add_f32_e32 v8, v8, v76
	v_add_f32_e32 v8, v8, v77
	ds_bpermute_b32 v9, v194, v8
	s_waitcnt vmcnt(0)
	v_lshlrev_b32_e32 v70, 16, v74
	v_and_b32_e32 v71, 0xffff0000, v74
	v_lshlrev_b32_e32 v72, 16, v75
	v_and_b32_e32 v73, 0xffff0000, v75
	s_waitcnt lgkmcnt(0)
	v_add_f32_e32 v8, v8, v9
	v_fmamk_f32 v8, v8, 0x3c000000, v195
	v_mul_f32_e32 v9, 0x4b800000, v8
	v_cmp_gt_f32_e32 vcc, s65, v8
	global_load_dwordx2 v[28:29], v[68:69], off offset:16
	global_load_dwordx2 v[30:31], v[68:69], off offset:32
	global_load_dwordx2 v[46:47], v[68:69], off offset:48
	v_cndmask_b32_e32 v8, v8, v9, vcc
	v_rsq_f32_e32 v10, v8
	v_lshl_add_u64 v[8:9], s[18:19], 0, v[130:131]
	v_lshl_add_u64 v[8:9], v[8:9], 0, v[158:159]
	v_mul_f32_e32 v11, 0x45800000, v10
	v_cndmask_b32_e32 v10, v10, v11, vcc
	v_mul_f32_e32 v10, 0x3f4ccccd, v10
	v_pk_mul_f32 v[48:49], v[48:49], v[10:11] op_sel_hi:[1,0]
	v_pk_mul_f32 v[42:43], v[42:43], v[10:11] op_sel_hi:[1,0]
	v_pk_mul_f32 v[12:13], v[12:13], v[48:49]
	v_pk_mul_f32 v[48:49], v[50:51], v[10:11] op_sel_hi:[1,0]
	v_pk_mul_f32 v[12:13], v[12:13], v[70:71]
	v_pk_mul_f32 v[14:15], v[14:15], v[48:49]
	v_cvt_pk_bf16_f32 v12, v12, v13
	v_pk_mul_f32 v[14:15], v[14:15], v[72:73]
	v_pk_mul_f32 v[50:51], v[78:79], v[10:11] op_sel_hi:[1,0]
	v_cvt_pk_bf16_f32 v13, v14, v15
	global_store_dwordx2 v[8:9], v[12:13], off sc1
	global_load_dwordx4 v[12:15], v156, s[40:41] offset:32
	v_pk_mul_f32 v[44:45], v[44:45], v[10:11] op_sel_hi:[1,0]
	v_pk_mul_f32 v[40:41], v[40:41], v[10:11] op_sel_hi:[1,0]
	v_pk_mul_f32 v[34:35], v[34:35], v[10:11] op_sel_hi:[1,0]
	v_pk_mul_f32 v[32:33], v[32:33], v[10:11] op_sel_hi:[1,0]
	v_pk_mul_f32 v[24:25], v[24:25], v[10:11] op_sel_hi:[1,0]
	v_pk_mul_f32 v[26:27], v[26:27], v[10:11] op_sel_hi:[1,0]
	v_pk_mul_f32 v[22:23], v[22:23], v[10:11] op_sel_hi:[1,0]
	v_pk_mul_f32 v[20:21], v[20:21], v[10:11] op_sel_hi:[1,0]
	v_pk_mul_f32 v[18:19], v[18:19], v[10:11] op_sel_hi:[1,0]
	v_pk_mul_f32 v[16:17], v[16:17], v[10:11] op_sel_hi:[1,0]
	v_pk_mul_f32 v[4:5], v[4:5], v[10:11] op_sel_hi:[1,0]
	v_pk_mul_f32 v[0:1], v[0:1], v[10:11] op_sel_hi:[1,0]
	v_pk_mul_f32 v[6:7], v[6:7], v[10:11] op_sel_hi:[1,0]
	v_pk_mul_f32 v[2:3], v[2:3], v[10:11] op_sel_hi:[1,0]
	s_waitcnt vmcnt(4)
	v_lshlrev_b32_e32 v48, 16, v28
	v_and_b32_e32 v49, 0xffff0000, v28
	v_lshlrev_b32_e32 v28, 16, v29
	v_and_b32_e32 v29, 0xffff0000, v29
	s_waitcnt vmcnt(0)
	v_pk_mul_f32 v[12:13], v[12:13], v[50:51]
	s_nop 0
	v_pk_mul_f32 v[12:13], v[12:13], v[48:49]
	v_pk_mul_f32 v[48:49], v[54:55], v[10:11] op_sel_hi:[1,0]
	v_cvt_pk_bf16_f32 v12, v12, v13
	v_pk_mul_f32 v[14:15], v[14:15], v[48:49]
	v_pk_mul_f32 v[48:49], v[80:81], v[10:11] op_sel_hi:[1,0]
	v_pk_mul_f32 v[14:15], v[14:15], v[28:29]
	v_pk_mul_f32 v[50:51], v[52:53], v[10:11] op_sel_hi:[1,0]
	v_cvt_pk_bf16_f32 v13, v14, v15
	global_store_dwordx2 v[8:9], v[12:13], off offset:16 sc1
	global_load_dwordx4 v[12:15], v156, s[40:41] offset:64
	v_lshlrev_b32_e32 v28, 16, v30
	v_and_b32_e32 v29, 0xffff0000, v30
	v_lshlrev_b32_e32 v30, 16, v31
	v_and_b32_e32 v31, 0xffff0000, v31
	v_pk_mul_f32 v[52:53], v[60:61], v[10:11] op_sel_hi:[1,0]
	v_pk_mul_f32 v[54:55], v[56:57], v[10:11] op_sel_hi:[1,0]
	s_waitcnt vmcnt(0)
	v_pk_mul_f32 v[12:13], v[48:49], v[12:13]
	v_pk_mul_f32 v[14:15], v[50:51], v[14:15]
	v_pk_mul_f32 v[12:13], v[12:13], v[28:29]
	v_pk_mul_f32 v[14:15], v[14:15], v[30:31]
	v_cvt_pk_bf16_f32 v12, v12, v13
	v_cvt_pk_bf16_f32 v13, v14, v15
	global_store_dwordx2 v[8:9], v[12:13], off offset:32 sc1
	global_load_dwordx4 v[12:15], v156, s[40:41] offset:96
	s_nop 0
	global_load_dwordx2 v[28:29], v[68:69], off offset:64
	v_pk_mul_f32 v[48:49], v[84:85], v[10:11] op_sel_hi:[1,0]
	v_pk_mul_f32 v[50:51], v[62:63], v[10:11] op_sel_hi:[1,0]
	v_lshlrev_b32_e32 v30, 16, v46
	v_and_b32_e32 v31, 0xffff0000, v46
	v_lshlrev_b32_e32 v46, 16, v47
	v_and_b32_e32 v47, 0xffff0000, v47
	s_waitcnt vmcnt(1)
	v_pk_mul_f32 v[12:13], v[48:49], v[12:13]
	v_pk_mul_f32 v[14:15], v[50:51], v[14:15]
	v_pk_mul_f32 v[12:13], v[12:13], v[30:31]
	v_pk_mul_f32 v[14:15], v[14:15], v[46:47]
	v_cvt_pk_bf16_f32 v12, v12, v13
	v_cvt_pk_bf16_f32 v13, v14, v15
	global_store_dwordx2 v[8:9], v[12:13], off offset:48 sc1
	global_load_dwordx4 v[12:15], v156, s[40:41] offset:128
	s_nop 0
	global_load_dwordx2 v[30:31], v[68:69], off offset:80
	global_load_dwordx2 v[46:47], v[68:69], off offset:96
	global_load_dwordx2 v[48:49], v[68:69], off offset:112
	s_waitcnt vmcnt(5)
	v_lshlrev_b32_e32 v50, 16, v28
	v_and_b32_e32 v51, 0xffff0000, v28
	v_lshlrev_b32_e32 v28, 16, v29
	v_and_b32_e32 v29, 0xffff0000, v29
	s_waitcnt vmcnt(3)
	v_pk_mul_f32 v[12:13], v[52:53], v[12:13]
	v_pk_mul_f32 v[14:15], v[54:55], v[14:15]
	v_pk_mul_f32 v[12:13], v[12:13], v[50:51]
	v_pk_mul_f32 v[14:15], v[14:15], v[28:29]
	v_cvt_pk_bf16_f32 v12, v12, v13
	v_cvt_pk_bf16_f32 v13, v14, v15
	global_store_dwordx2 v[8:9], v[12:13], off offset:64 sc1
	global_load_dwordx4 v[12:15], v156, s[40:41] offset:160
	v_pk_mul_f32 v[50:51], v[82:83], v[10:11] op_sel_hi:[1,0]
	v_pk_mul_f32 v[52:53], v[58:59], v[10:11] op_sel_hi:[1,0]
	s_waitcnt vmcnt(4)
	v_lshlrev_b32_e32 v28, 16, v30
	v_and_b32_e32 v29, 0xffff0000, v30
	v_lshlrev_b32_e32 v30, 16, v31
	v_and_b32_e32 v31, 0xffff0000, v31
	s_waitcnt vmcnt(0)
	v_pk_mul_f32 v[12:13], v[50:51], v[12:13]
	v_pk_mul_f32 v[14:15], v[52:53], v[14:15]
	v_pk_mul_f32 v[12:13], v[12:13], v[28:29]
	v_pk_mul_f32 v[14:15], v[14:15], v[30:31]
	v_cvt_pk_bf16_f32 v12, v12, v13
	v_cvt_pk_bf16_f32 v13, v14, v15
	global_store_dwordx2 v[8:9], v[12:13], off offset:80 sc1
	global_load_dwordx4 v[12:15], v156, s[40:41] offset:192
	v_lshlrev_b32_e32 v28, 16, v46
	v_and_b32_e32 v29, 0xffff0000, v46
	v_lshlrev_b32_e32 v30, 16, v47
	v_and_b32_e32 v31, 0xffff0000, v47
	v_pk_mul_f32 v[46:47], v[86:87], v[10:11] op_sel_hi:[1,0]
	s_waitcnt vmcnt(0)
	v_pk_mul_f32 v[14:15], v[42:43], v[14:15]
	v_pk_mul_f32 v[12:13], v[46:47], v[12:13]
	v_pk_mul_f32 v[14:15], v[14:15], v[30:31]
	v_pk_mul_f32 v[12:13], v[12:13], v[28:29]
	v_lshlrev_b32_e32 v30, 16, v48
	v_cvt_pk_bf16_f32 v12, v12, v13
	v_cvt_pk_bf16_f32 v13, v14, v15
	global_store_dwordx2 v[8:9], v[12:13], off offset:96 sc1
	global_load_dwordx4 v[12:15], v156, s[40:41] offset:224
	s_nop 0
	global_load_dwordx2 v[28:29], v[68:69], off offset:128
	v_and_b32_e32 v31, 0xffff0000, v48
	v_lshlrev_b32_e32 v42, 16, v49
	v_and_b32_e32 v43, 0xffff0000, v49
	s_waitcnt vmcnt(1)
	v_pk_mul_f32 v[12:13], v[44:45], v[12:13]
	v_pk_mul_f32 v[14:15], v[40:41], v[14:15]
	v_pk_mul_f32 v[12:13], v[12:13], v[30:31]
	v_pk_mul_f32 v[14:15], v[14:15], v[42:43]
	v_cvt_pk_bf16_f32 v12, v12, v13
	v_cvt_pk_bf16_f32 v13, v14, v15
	global_store_dwordx2 v[8:9], v[12:13], off offset:112 sc1
	global_load_dwordx4 v[12:15], v156, s[40:41] offset:256
	s_nop 0
	global_load_dwordx2 v[30:31], v[68:69], off offset:144
	global_load_dwordx2 v[40:41], v[68:69], off offset:160
	global_load_dwordx2 v[42:43], v[68:69], off offset:176
	s_waitcnt vmcnt(5)
	v_lshlrev_b32_e32 v44, 16, v28
	v_and_b32_e32 v45, 0xffff0000, v28
	v_lshlrev_b32_e32 v28, 16, v29
	v_and_b32_e32 v29, 0xffff0000, v29
	s_waitcnt vmcnt(3)
	v_pk_mul_f32 v[12:13], v[34:35], v[12:13]
	v_pk_mul_f32 v[14:15], v[32:33], v[14:15]
	v_pk_mul_f32 v[12:13], v[12:13], v[44:45]
	v_pk_mul_f32 v[14:15], v[14:15], v[28:29]
	v_cvt_pk_bf16_f32 v12, v12, v13
	v_cvt_pk_bf16_f32 v13, v14, v15
	global_store_dwordx2 v[8:9], v[12:13], off offset:128 sc1
	global_load_dwordx4 v[12:15], v156, s[40:41] offset:288
	v_pk_mul_f32 v[32:33], v[38:39], v[10:11] op_sel_hi:[1,0]
	v_pk_mul_f32 v[34:35], v[36:37], v[10:11] op_sel_hi:[1,0]
	s_waitcnt vmcnt(4)
	v_lshlrev_b32_e32 v28, 16, v30
	v_and_b32_e32 v29, 0xffff0000, v30
	v_lshlrev_b32_e32 v30, 16, v31
	v_and_b32_e32 v31, 0xffff0000, v31
	s_waitcnt vmcnt(0)
	v_pk_mul_f32 v[12:13], v[32:33], v[12:13]
	v_pk_mul_f32 v[14:15], v[34:35], v[14:15]
	v_pk_mul_f32 v[12:13], v[12:13], v[28:29]
	v_pk_mul_f32 v[14:15], v[14:15], v[30:31]
	v_cvt_pk_bf16_f32 v12, v12, v13
	v_cvt_pk_bf16_f32 v13, v14, v15
	global_store_dwordx2 v[8:9], v[12:13], off offset:144 sc1
	global_load_dwordx4 v[12:15], v156, s[40:41] offset:320
	v_lshlrev_b32_e32 v28, 16, v40
	v_and_b32_e32 v29, 0xffff0000, v40
	v_lshlrev_b32_e32 v30, 16, v41
	v_and_b32_e32 v31, 0xffff0000, v41
	s_waitcnt vmcnt(0)
	v_pk_mul_f32 v[12:13], v[24:25], v[12:13]
	v_pk_mul_f32 v[14:15], v[26:27], v[14:15]
	v_pk_mul_f32 v[12:13], v[12:13], v[28:29]
	v_pk_mul_f32 v[14:15], v[14:15], v[30:31]
	v_cvt_pk_bf16_f32 v12, v12, v13
	v_cvt_pk_bf16_f32 v13, v14, v15
	global_store_dwordx2 v[8:9], v[12:13], off offset:160 sc1
	global_load_dwordx4 v[12:15], v156, s[40:41] offset:352
	s_nop 0
	global_load_dwordx2 v[24:25], v[68:69], off offset:192
	v_lshlrev_b32_e32 v26, 16, v42
	v_and_b32_e32 v27, 0xffff0000, v42
	v_lshlrev_b32_e32 v28, 16, v43
	v_and_b32_e32 v29, 0xffff0000, v43
	s_waitcnt vmcnt(1)
	v_pk_mul_f32 v[12:13], v[22:23], v[12:13]
	v_pk_mul_f32 v[14:15], v[20:21], v[14:15]
	v_pk_mul_f32 v[12:13], v[12:13], v[26:27]
	v_pk_mul_f32 v[14:15], v[14:15], v[28:29]
	v_cvt_pk_bf16_f32 v12, v12, v13
	v_cvt_pk_bf16_f32 v13, v14, v15
	global_store_dwordx2 v[8:9], v[12:13], off offset:176 sc1
	global_load_dwordx4 v[12:15], v156, s[40:41] offset:384
	s_nop 0
	global_load_dwordx2 v[20:21], v[68:69], off offset:208
	global_load_dwordx2 v[22:23], v[68:69], off offset:224
	global_load_dwordx2 v[26:27], v[68:69], off offset:240
	s_waitcnt vmcnt(5)
	v_lshlrev_b32_e32 v28, 16, v24
	v_and_b32_e32 v29, 0xffff0000, v24
	v_lshlrev_b32_e32 v24, 16, v25
	v_and_b32_e32 v25, 0xffff0000, v25
	s_waitcnt vmcnt(3)
	v_pk_mul_f32 v[12:13], v[18:19], v[12:13]
	v_pk_mul_f32 v[14:15], v[16:17], v[14:15]
	v_pk_mul_f32 v[12:13], v[12:13], v[28:29]
	v_pk_mul_f32 v[14:15], v[14:15], v[24:25]
	v_cvt_pk_bf16_f32 v12, v12, v13
	v_cvt_pk_bf16_f32 v13, v14, v15
	global_store_dwordx2 v[8:9], v[12:13], off offset:192 sc1
	global_load_dwordx4 v[12:15], v156, s[40:41] offset:416
	s_waitcnt vmcnt(4)
	v_lshlrev_b32_e32 v16, 16, v20
	v_and_b32_e32 v17, 0xffff0000, v20
	v_lshlrev_b32_e32 v18, 16, v21
	v_and_b32_e32 v19, 0xffff0000, v21
	s_waitcnt vmcnt(0)
	v_pk_mul_f32 v[4:5], v[4:5], v[12:13]
	v_pk_mul_f32 v[0:1], v[0:1], v[14:15]
	v_pk_mul_f32 v[4:5], v[4:5], v[16:17]
	v_pk_mul_f32 v[0:1], v[0:1], v[18:19]
	v_cvt_pk_bf16_f32 v4, v4, v5
	v_cvt_pk_bf16_f32 v5, v0, v1
	global_store_dwordx2 v[8:9], v[4:5], off offset:208 sc1
	global_load_dwordx4 v[12:15], v156, s[40:41] offset:448
	v_lshlrev_b32_e32 v0, 16, v22
	v_and_b32_e32 v1, 0xffff0000, v22
	v_lshlrev_b32_e32 v4, 16, v23
	v_and_b32_e32 v5, 0xffff0000, v23
	s_waitcnt vmcnt(0)
	v_pk_mul_f32 v[6:7], v[6:7], v[12:13]
	v_pk_mul_f32 v[2:3], v[2:3], v[14:15]
	v_pk_mul_f32 v[0:1], v[6:7], v[0:1]
	v_pk_mul_f32 v[2:3], v[2:3], v[4:5]
	v_cvt_pk_bf16_f32 v0, v0, v1
	v_cvt_pk_bf16_f32 v1, v2, v3
	global_store_dwordx2 v[8:9], v[0:1], off offset:224 sc1
	global_load_dwordx4 v[0:3], v156, s[40:41] offset:480
	v_pk_mul_f32 v[12:13], v[64:65], v[10:11] op_sel_hi:[1,0]
	v_pk_mul_f32 v[10:11], v[66:67], v[10:11] op_sel_hi:[1,0]
	v_lshlrev_b32_e32 v4, 16, v26
	v_and_b32_e32 v5, 0xffff0000, v26
	v_lshlrev_b32_e32 v6, 16, v27
	v_and_b32_e32 v7, 0xffff0000, v27
	s_waitcnt vmcnt(0)
	v_pk_mul_f32 v[0:1], v[12:13], v[0:1]
	v_pk_mul_f32 v[2:3], v[10:11], v[2:3]
	v_pk_mul_f32 v[0:1], v[0:1], v[4:5]
	v_pk_mul_f32 v[2:3], v[2:3], v[6:7]
	v_cvt_pk_bf16_f32 v0, v0, v1
	v_cvt_pk_bf16_f32 v1, v2, v3
	global_store_dwordx2 v[8:9], v[0:1], off offset:240 sc1

.LBB0_285:
	v_lshl_add_u64 v[74:75], v[190:191], 0, s[20:21]
	v_lshlrev_b64 v[74:75], 10, v[74:75]
	v_lshl_add_u64 v[74:75], v[74:75], 0, s[22:23]
	v_lshlrev_b64 v[74:75], 1, v[74:75]
	v_lshl_add_u64 v[76:77], v[186:187], 0, v[74:75]
	global_load_dwordx2 v[78:79], v[76:77], off
	global_load_dwordx2 v[80:81], v[76:77], off offset:16
	global_load_dwordx2 v[82:83], v[76:77], off offset:32
	global_load_dwordx2 v[84:85], v[76:77], off offset:48
	global_load_dwordx2 v[86:87], v[76:77], off offset:64
	global_load_dwordx2 v[88:89], v[76:77], off offset:80
	global_load_dwordx2 v[90:91], v[76:77], off offset:96
	v_div_scale_f32 v92, s[26:27], v70, v70, 1.0
	global_load_dwordx2 v[76:77], v[76:77], off offset:112
	v_rcp_f32_e32 v93, v92
	v_div_scale_f32 v94, vcc, 1.0, v70, 1.0
	v_lshl_add_u64 v[74:75], v[188:189], 0, v[74:75]
	v_fma_f32 v95, -v92, v93, 1.0
	v_fmac_f32_e32 v93, v95, v93
	v_mul_f32_e32 v95, v94, v93
	v_fma_f32 v96, -v92, v95, v94
	v_fmac_f32_e32 v95, v96, v93
	v_fma_f32 v92, -v92, v95, v94
	v_div_fmas_f32 v92, v92, v93, v95
	v_div_fixup_f32 v92, v92, v70, 1.0
	v_pk_mul_f32 v[94:95], v[48:49], v[92:93] op_sel_hi:[1,0]
	v_pk_mul_f32 v[96:97], v[50:51], v[92:93] op_sel_hi:[1,0]
	v_pk_mul_f32 v[98:99], v[52:53], v[92:93] op_sel_hi:[1,0]
	v_pk_mul_f32 v[100:101], v[54:55], v[92:93] op_sel_hi:[1,0]
	v_pk_mul_f32 v[102:103], v[56:57], v[92:93] op_sel_hi:[1,0]
	s_waitcnt vmcnt(9)
	v_pk_mul_f32 v[104:105], v[58:59], v[92:93] op_sel_hi:[1,0]
	v_pk_mul_f32 v[106:107], v[60:61], v[92:93] op_sel_hi:[1,0]
	s_waitcnt vmcnt(8)
	v_pk_mul_f32 v[108:109], v[62:63], v[92:93] op_sel_hi:[1,0]
	v_pk_mul_f32 v[110:111], v[32:33], v[92:93] op_sel_hi:[1,0]
	v_pk_mul_f32 v[112:113], v[34:35], v[92:93] op_sel_hi:[1,0]
	v_pk_mul_f32 v[116:117], v[38:39], v[92:93] op_sel_hi:[1,0]
	v_pk_mul_f32 v[114:115], v[36:37], v[92:93] op_sel_hi:[1,0]
	s_waitcnt vmcnt(7)
	v_lshlrev_b32_e32 v118, 16, v78
	v_and_b32_e32 v119, 0xffff0000, v78
	v_lshlrev_b32_e32 v78, 16, v79
	v_and_b32_e32 v79, 0xffff0000, v79
	s_waitcnt vmcnt(6)
	v_lshlrev_b32_e32 v120, 16, v80
	v_and_b32_e32 v121, 0xffff0000, v80
	v_lshlrev_b32_e32 v80, 16, v81
	v_and_b32_e32 v81, 0xffff0000, v81
	s_waitcnt vmcnt(5)
	v_lshlrev_b32_e32 v122, 16, v82
	v_and_b32_e32 v123, 0xffff0000, v82
	v_lshlrev_b32_e32 v82, 16, v83
	v_and_b32_e32 v83, 0xffff0000, v83
	s_waitcnt vmcnt(4)
	v_lshlrev_b32_e32 v124, 16, v84
	v_and_b32_e32 v125, 0xffff0000, v84
	v_lshlrev_b32_e32 v84, 16, v85
	v_and_b32_e32 v85, 0xffff0000, v85
	s_waitcnt vmcnt(3)
	v_lshlrev_b32_e32 v126, 16, v86
	v_and_b32_e32 v127, 0xffff0000, v86
	v_lshlrev_b32_e32 v86, 16, v87
	v_and_b32_e32 v87, 0xffff0000, v87
	v_pk_mul_f32 v[94:95], v[94:95], v[118:119]
	v_pk_mul_f32 v[78:79], v[96:97], v[78:79]
	v_pk_mul_f32 v[96:97], v[98:99], v[120:121]
	v_pk_mul_f32 v[80:81], v[100:101], v[80:81]
	v_pk_mul_f32 v[98:99], v[102:103], v[122:123]
	v_pk_mul_f32 v[82:83], v[104:105], v[82:83]
	v_pk_mul_f32 v[100:101], v[106:107], v[124:125]
	v_pk_mul_f32 v[84:85], v[108:109], v[84:85]
	v_pk_mul_f32 v[102:103], v[110:111], v[126:127]
	v_pk_mul_f32 v[86:87], v[112:113], v[86:87]
	v_cvt_pk_bf16_f32 v94, v94, v95
	v_cvt_pk_bf16_f32 v95, v78, v79
	v_cvt_pk_bf16_f32 v78, v96, v97
	v_cvt_pk_bf16_f32 v79, v80, v81
	v_cvt_pk_bf16_f32 v80, v98, v99
	v_cvt_pk_bf16_f32 v81, v82, v83
	v_cvt_pk_bf16_f32 v82, v100, v101
	v_cvt_pk_bf16_f32 v83, v84, v85
	v_cvt_pk_bf16_f32 v84, v102, v103
	v_cvt_pk_bf16_f32 v85, v86, v87
	global_store_dwordx2 v[74:75], v[94:95], off sc1
	global_store_dwordx2 v[74:75], v[78:79], off offset:16 sc1
	global_store_dwordx2 v[74:75], v[80:81], off offset:32 sc1
	global_store_dwordx2 v[74:75], v[82:83], off offset:48 sc1
	global_store_dwordx2 v[74:75], v[84:85], off offset:64 sc1
	s_waitcnt vmcnt(7)
	v_lshlrev_b32_e32 v78, 16, v89
	v_and_b32_e32 v79, 0xffff0000, v89
	v_pk_mul_f32 v[78:79], v[116:117], v[78:79]
	s_waitcnt vmcnt(6)
	v_lshlrev_b32_e32 v80, 16, v90
	v_cvt_pk_bf16_f32 v87, v78, v79
	v_pk_mul_f32 v[78:79], v[40:41], v[92:93] op_sel_hi:[1,0]
	v_and_b32_e32 v81, 0xffff0000, v90
	v_pk_mul_f32 v[78:79], v[78:79], v[80:81]
	v_pk_mul_f32 v[80:81], v[42:43], v[92:93] op_sel_hi:[1,0]
	v_lshlrev_b32_e32 v82, 16, v91
	v_and_b32_e32 v83, 0xffff0000, v91
	v_pk_mul_f32 v[80:81], v[80:81], v[82:83]
	v_cvt_pk_bf16_f32 v78, v78, v79
	v_cvt_pk_bf16_f32 v79, v80, v81
	global_store_dwordx2 v[74:75], v[78:79], off offset:96 sc1
	v_pk_mul_f32 v[78:79], v[44:45], v[92:93] op_sel_hi:[1,0]
	s_waitcnt vmcnt(6)
	v_lshlrev_b32_e32 v80, 16, v76
	v_and_b32_e32 v81, 0xffff0000, v76
	v_pk_mul_f32 v[78:79], v[78:79], v[80:81]
	v_lshlrev_b32_e32 v132, 16, v88
	v_and_b32_e32 v133, 0xffff0000, v88
	v_cvt_pk_bf16_f32 v76, v78, v79
	v_pk_mul_f32 v[78:79], v[46:47], v[92:93] op_sel_hi:[1,0]
	v_lshlrev_b32_e32 v80, 16, v77
	v_and_b32_e32 v81, 0xffff0000, v77
	v_pk_mul_f32 v[104:105], v[114:115], v[132:133]
	v_pk_mul_f32 v[78:79], v[78:79], v[80:81]
	v_cvt_pk_bf16_f32 v86, v104, v105
	v_cvt_pk_bf16_f32 v77, v78, v79
	global_store_dwordx2 v[74:75], v[86:87], off offset:80 sc1
	global_store_dwordx2 v[74:75], v[76:77], off offset:112 sc1
	s_cbranch_execnz .LBB0_282

.LBB0_309:
	s_cmpk_gt_u32 s36, 0xff
	s_waitcnt lgkmcnt(0)
	s_barrier
	s_cbranch_scc1 .LBB0_244
	ds_read2st64_b32 v[80:81], v64 offset1:1
	ds_read2st64_b32 v[82:83], v64 offset0:2 offset1:3
	ds_read2st64_b32 v[84:85], v64 offset0:4 offset1:5
	ds_read2st64_b32 v[86:87], v64 offset0:6 offset1:7
	ds_read2st64_b32 v[88:89], v64 offset0:8 offset1:9
	ds_read2st64_b32 v[128:129], v64 offset0:10 offset1:11
	ds_read2st64_b32 v[132:133], v64 offset0:12 offset1:13
	ds_read2st64_b32 v[134:135], v64 offset0:14 offset1:15
	ds_read2st64_b32 v[136:137], v64 offset0:16 offset1:17
	ds_read2st64_b32 v[138:139], v64 offset0:18 offset1:19
	ds_read2st64_b32 v[140:141], v64 offset0:20 offset1:21
	ds_read2st64_b32 v[142:143], v64 offset0:22 offset1:23
	ds_read2st64_b32 v[144:145], v64 offset0:24 offset1:25
	ds_read2st64_b32 v[146:147], v64 offset0:26 offset1:27
	ds_read2st64_b32 v[126:127], v64 offset0:28 offset1:29
	ds_read2st64_b32 v[148:149], v64 offset0:30 offset1:31
	ds_read2st64_b32 v[118:119], v64 offset0:32 offset1:33
	ds_read2st64_b32 v[122:123], v64 offset0:34 offset1:35
	ds_read2st64_b32 v[108:109], v64 offset0:36 offset1:37
	ds_read2st64_b32 v[116:117], v64 offset0:38 offset1:39
	ds_read2st64_b32 v[96:97], v64 offset0:40 offset1:41
	ds_read2st64_b32 v[102:103], v64 offset0:42 offset1:43
	ds_read2st64_b32 v[94:95], v64 offset0:44 offset1:45
	ds_read2st64_b32 v[98:99], v64 offset0:46 offset1:47
	ds_read2st64_b32 v[90:91], v64 offset0:56 offset1:57
	ds_read2st64_b32 v[92:93], v64 offset0:58 offset1:59
	ds_read2st64_b32 v[66:67], v64 offset0:60 offset1:61
	ds_read2st64_b32 v[68:69], v64 offset0:62 offset1:63
	ds_read2st64_b32 v[106:107], v64 offset0:48 offset1:49
	ds_read2st64_b32 v[112:113], v64 offset0:50 offset1:51
	ds_read2st64_b32 v[100:101], v64 offset0:52 offset1:53
	ds_read2st64_b32 v[104:105], v64 offset0:54 offset1:55
	s_waitcnt lgkmcnt(14)
	v_pk_mul_f32 v[80:81], v[180:181], v[80:81]
	v_pk_mul_f32 v[82:83], v[180:181], v[82:83]
	v_pk_fma_f32 v[48:49], v[48:49], v[70:71], v[80:81] op_sel_hi:[1,0,1] neg_lo:[0,0,1] neg_hi:[0,0,1]
	v_pk_mul_f32 v[80:81], v[180:181], v[86:87]
	v_pk_fma_f32 v[50:51], v[50:51], v[70:71], v[82:83] op_sel_hi:[1,0,1] neg_lo:[0,0,1] neg_hi:[0,0,1]
	v_pk_fma_f32 v[54:55], v[54:55], v[70:71], v[80:81] op_sel_hi:[1,0,1] neg_lo:[0,0,1] neg_hi:[0,0,1]
	v_pk_mul_f32 v[80:81], v[180:181], v[84:85]
	s_lshl_b32 s4, s27, 23
	v_pk_fma_f32 v[80:81], v[52:53], v[70:71], v[80:81] op_sel_hi:[1,0,1] neg_lo:[0,0,1] neg_hi:[0,0,1]
	v_pk_mul_f32 v[52:53], v[180:181], v[128:129]
	s_lshl_b32 s5, s26, 7
	v_pk_fma_f32 v[52:53], v[58:59], v[70:71], v[52:53] op_sel_hi:[1,0,1] neg_lo:[0,0,1] neg_hi:[0,0,1]
	v_pk_mul_f32 v[58:59], v[180:181], v[88:89]
	s_add_i32 s5, s5, s4
	v_pk_fma_f32 v[82:83], v[56:57], v[70:71], v[58:59] op_sel_hi:[1,0,1] neg_lo:[0,0,1] neg_hi:[0,0,1]
	v_pk_mul_f32 v[56:57], v[180:181], v[134:135]
	v_lshl_add_u32 v130, v159, 10, s5
	v_pk_fma_f32 v[62:63], v[62:63], v[70:71], v[56:57] op_sel_hi:[1,0,1] neg_lo:[0,0,1] neg_hi:[0,0,1]
	v_pk_mul_f32 v[56:57], v[180:181], v[132:133]
	s_waitcnt lgkmcnt(5)
	v_pk_mul_f32 v[64:65], v[180:181], v[66:67]
	v_pk_fma_f32 v[86:87], v[60:61], v[70:71], v[56:57] op_sel_hi:[1,0,1] neg_lo:[0,0,1] neg_hi:[0,0,1]
	v_pk_mul_f32 v[56:57], v[180:181], v[138:139]
	v_lshlrev_b64 v[72:73], 1, v[130:131]
	v_pk_fma_f32 v[56:57], v[34:35], v[70:71], v[56:57] op_sel_hi:[1,0,1] neg_lo:[0,0,1] neg_hi:[0,0,1]
	v_pk_mul_f32 v[34:35], v[180:181], v[136:137]
	v_pk_fma_f32 v[64:65], v[12:13], v[70:71], v[64:65] op_sel_hi:[1,0,1] neg_lo:[0,0,1] neg_hi:[0,0,1]
	v_pk_fma_f32 v[60:61], v[32:33], v[70:71], v[34:35] op_sel_hi:[1,0,1] neg_lo:[0,0,1] neg_hi:[0,0,1]
	v_pk_mul_f32 v[32:33], v[180:181], v[142:143]
	s_waitcnt lgkmcnt(4)
	v_pk_mul_f32 v[12:13], v[180:181], v[68:69]
	v_pk_fma_f32 v[58:59], v[38:39], v[70:71], v[32:33] op_sel_hi:[1,0,1] neg_lo:[0,0,1] neg_hi:[0,0,1]
	v_pk_mul_f32 v[32:33], v[180:181], v[140:141]
	v_lshl_add_u64 v[68:69], s[16:17], 0, v[72:73]
	v_pk_fma_f32 v[84:85], v[36:37], v[70:71], v[32:33] op_sel_hi:[1,0,1] neg_lo:[0,0,1] neg_hi:[0,0,1]
	v_pk_mul_f32 v[32:33], v[180:181], v[146:147]
	v_mov_b32_e32 v159, v131
	v_pk_fma_f32 v[42:43], v[42:43], v[70:71], v[32:33] op_sel_hi:[1,0,1] neg_lo:[0,0,1] neg_hi:[0,0,1]
	v_pk_mul_f32 v[32:33], v[180:181], v[144:145]
	v_pk_mul_f32 v[114:115], v[48:49], v[48:49]
	v_pk_fma_f32 v[88:89], v[40:41], v[70:71], v[32:33] op_sel_hi:[1,0,1] neg_lo:[0,0,1] neg_hi:[0,0,1]
	v_pk_mul_f32 v[32:33], v[180:181], v[148:149]
	v_pk_fma_f32 v[66:67], v[14:15], v[70:71], v[12:13] op_sel_hi:[1,0,1] neg_lo:[0,0,1] neg_hi:[0,0,1]
	v_pk_fma_f32 v[40:41], v[46:47], v[70:71], v[32:33] op_sel_hi:[1,0,1] neg_lo:[0,0,1] neg_hi:[0,0,1]
	v_pk_mul_f32 v[32:33], v[180:181], v[126:127]
	global_load_dwordx4 v[12:15], v156, s[40:41]
	v_pk_fma_f32 v[44:45], v[44:45], v[70:71], v[32:33] op_sel_hi:[1,0,1] neg_lo:[0,0,1] neg_hi:[0,0,1]
	v_pk_mul_f32 v[32:33], v[180:181], v[122:123]
	v_lshl_add_u64 v[68:69], v[68:69], 0, v[158:159]
	v_pk_fma_f32 v[32:33], v[18:19], v[70:71], v[32:33] op_sel_hi:[1,0,1] neg_lo:[0,0,1] neg_hi:[0,0,1]
	v_pk_mul_f32 v[18:19], v[180:181], v[118:119]
	v_pk_mul_f32 v[110:111], v[50:51], v[50:51]
	v_pk_fma_f32 v[34:35], v[16:17], v[70:71], v[18:19] op_sel_hi:[1,0,1] neg_lo:[0,0,1] neg_hi:[0,0,1]
	v_pk_mul_f32 v[16:17], v[180:181], v[116:117]
	global_load_dwordx2 v[76:77], v[68:69], off
	v_pk_fma_f32 v[36:37], v[22:23], v[70:71], v[16:17] op_sel_hi:[1,0,1] neg_lo:[0,0,1] neg_hi:[0,0,1]
	v_pk_mul_f32 v[16:17], v[180:181], v[108:109]
	v_pk_mul_f32 v[124:125], v[80:81], v[80:81]
	v_pk_fma_f32 v[38:39], v[20:21], v[70:71], v[16:17] op_sel_hi:[1,0,1] neg_lo:[0,0,1] neg_hi:[0,0,1]
	v_pk_mul_f32 v[16:17], v[180:181], v[102:103]
	v_pk_mul_f32 v[120:121], v[54:55], v[54:55]
	v_pk_fma_f32 v[26:27], v[26:27], v[70:71], v[16:17] op_sel_hi:[1,0,1] neg_lo:[0,0,1] neg_hi:[0,0,1]
	v_pk_mul_f32 v[16:17], v[180:181], v[96:97]
	v_pk_mul_f32 v[150:151], v[82:83], v[82:83]
	v_pk_fma_f32 v[24:25], v[24:25], v[70:71], v[16:17] op_sel_hi:[1,0,1] neg_lo:[0,0,1] neg_hi:[0,0,1]
	v_pk_mul_f32 v[16:17], v[180:181], v[98:99]
	v_pk_mul_f32 v[128:129], v[52:53], v[52:53]
	v_pk_fma_f32 v[20:21], v[30:31], v[70:71], v[16:17] op_sel_hi:[1,0,1] neg_lo:[0,0,1] neg_hi:[0,0,1]
	v_pk_mul_f32 v[16:17], v[180:181], v[94:95]
	v_pk_mul_f32 v[132:133], v[86:87], v[86:87]
	v_pk_fma_f32 v[22:23], v[28:29], v[70:71], v[16:17] op_sel_hi:[1,0,1] neg_lo:[0,0,1] neg_hi:[0,0,1]
	s_waitcnt lgkmcnt(2)
	v_pk_mul_f32 v[16:17], v[180:181], v[112:113]
	v_pk_mul_f32 v[134:135], v[62:63], v[62:63]
	v_pk_fma_f32 v[16:17], v[2:3], v[70:71], v[16:17] op_sel_hi:[1,0,1] neg_lo:[0,0,1] neg_hi:[0,0,1]
	v_pk_mul_f32 v[2:3], v[180:181], v[106:107]
	v_pk_mul_f32 v[136:137], v[60:61], v[60:61]
	v_pk_fma_f32 v[18:19], v[0:1], v[70:71], v[2:3] op_sel_hi:[1,0,1] neg_lo:[0,0,1] neg_hi:[0,0,1]
	s_waitcnt lgkmcnt(0)
	v_pk_mul_f32 v[0:1], v[180:181], v[104:105]
	v_pk_mul_f32 v[2:3], v[180:181], v[100:101]
	v_pk_fma_f32 v[0:1], v[6:7], v[70:71], v[0:1] op_sel_hi:[1,0,1] neg_lo:[0,0,1] neg_hi:[0,0,1]
	v_pk_fma_f32 v[4:5], v[4:5], v[70:71], v[2:3] op_sel_hi:[1,0,1] neg_lo:[0,0,1] neg_hi:[0,0,1]
	v_pk_mul_f32 v[2:3], v[180:181], v[92:93]
	v_pk_mul_f32 v[6:7], v[180:181], v[90:91]
	v_pk_fma_f32 v[2:3], v[10:11], v[70:71], v[2:3] op_sel_hi:[1,0,1] neg_lo:[0,0,1] neg_hi:[0,0,1]
	v_pk_fma_f32 v[6:7], v[8:9], v[70:71], v[6:7] op_sel_hi:[1,0,1] neg_lo:[0,0,1] neg_hi:[0,0,1]
	v_add_f32_e32 v70, v114, v115
	v_add_f32_e32 v70, v70, v110
	v_add_f32_e32 v70, v70, v111
	v_add_f32_e32 v70, v70, v124
	v_add_f32_e32 v70, v70, v125
	v_add_f32_e32 v70, v70, v120
	v_add_f32_e32 v70, v70, v121
	v_add_f32_e32 v70, v70, v150
	v_add_f32_e32 v70, v70, v151
	v_add_f32_e32 v70, v70, v128
	v_add_f32_e32 v70, v70, v129
	v_add_f32_e32 v70, v70, v132
	v_add_f32_e32 v70, v70, v133
	v_add_f32_e32 v70, v70, v134
	v_add_f32_e32 v70, v70, v135
	v_add_f32_e32 v70, v70, v136
	v_pk_mul_f32 v[138:139], v[56:57], v[56:57]
	v_add_f32_e32 v70, v70, v137
	v_add_f32_e32 v70, v70, v138
	v_pk_mul_f32 v[140:141], v[84:85], v[84:85]
	v_add_f32_e32 v70, v70, v139
	v_add_f32_e32 v70, v70, v140
	v_pk_mul_f32 v[142:143], v[58:59], v[58:59]
	v_add_f32_e32 v70, v70, v141
	v_add_f32_e32 v70, v70, v142
	v_pk_mul_f32 v[144:145], v[88:89], v[88:89]
	v_add_f32_e32 v70, v70, v143
	v_add_f32_e32 v70, v70, v144
	v_pk_mul_f32 v[146:147], v[42:43], v[42:43]
	v_add_f32_e32 v70, v70, v145
	v_add_f32_e32 v70, v70, v146
	v_pk_mul_f32 v[126:127], v[44:45], v[44:45]
	v_add_f32_e32 v70, v70, v147
	v_add_f32_e32 v70, v70, v126
	v_pk_mul_f32 v[46:47], v[40:41], v[40:41]
	v_add_f32_e32 v70, v70, v127
	v_add_f32_e32 v46, v70, v46
	v_pk_mul_f32 v[118:119], v[34:35], v[34:35]
	v_add_f32_e32 v46, v46, v47
	v_add_f32_e32 v46, v46, v118
	v_pk_mul_f32 v[122:123], v[32:33], v[32:33]
	v_add_f32_e32 v46, v46, v119
	v_add_f32_e32 v46, v46, v122
	v_pk_mul_f32 v[108:109], v[38:39], v[38:39]
	v_add_f32_e32 v46, v46, v123
	v_add_f32_e32 v46, v46, v108
	v_pk_mul_f32 v[116:117], v[36:37], v[36:37]
	v_add_f32_e32 v46, v46, v109
	v_add_f32_e32 v46, v46, v116
	v_pk_mul_f32 v[96:97], v[24:25], v[24:25]
	v_add_f32_e32 v46, v46, v117
	v_add_f32_e32 v46, v46, v96
	v_pk_mul_f32 v[102:103], v[26:27], v[26:27]
	v_add_f32_e32 v46, v46, v97
	v_add_f32_e32 v46, v46, v102
	v_pk_mul_f32 v[28:29], v[22:23], v[22:23]
	v_add_f32_e32 v46, v46, v103
	v_add_f32_e32 v28, v46, v28
	v_pk_mul_f32 v[30:31], v[20:21], v[20:21]
	v_add_f32_e32 v28, v28, v29
	v_add_f32_e32 v28, v28, v30
	v_pk_mul_f32 v[98:99], v[18:19], v[18:19]
	v_add_f32_e32 v28, v28, v31
	v_add_f32_e32 v28, v28, v98
	v_pk_mul_f32 v[94:95], v[16:17], v[16:17]
	v_add_f32_e32 v28, v28, v99
	v_add_f32_e32 v28, v28, v94
	v_pk_mul_f32 v[100:101], v[4:5], v[4:5]
	v_add_f32_e32 v28, v28, v95
	v_add_f32_e32 v28, v28, v100
	v_pk_mul_f32 v[104:105], v[0:1], v[0:1]
	v_add_f32_e32 v28, v28, v101
	v_add_f32_e32 v28, v28, v104
	v_pk_mul_f32 v[8:9], v[6:7], v[6:7]
	v_add_f32_e32 v28, v28, v105
	v_add_f32_e32 v8, v28, v8
	v_pk_mul_f32 v[10:11], v[2:3], v[2:3]
	v_add_f32_e32 v8, v8, v9
	v_add_f32_e32 v8, v8, v10
	v_pk_mul_f32 v[74:75], v[64:65], v[64:65]
	v_add_f32_e32 v8, v8, v11
	v_add_f32_e32 v8, v8, v74
	v_pk_mul_f32 v[78:79], v[66:67], v[66:67]
	v_add_f32_e32 v8, v8, v75
	v_add_f32_e32 v8, v8, v78
	v_add_f32_e32 v8, v8, v79
	ds_bpermute_b32 v9, v194, v8
	s_waitcnt vmcnt(0)
	v_lshlrev_b32_e32 v70, 16, v76
	v_and_b32_e32 v71, 0xffff0000, v76
	v_lshlrev_b32_e32 v74, 16, v77
	v_and_b32_e32 v75, 0xffff0000, v77
	s_waitcnt lgkmcnt(0)
	v_add_f32_e32 v8, v8, v9
	v_fmamk_f32 v8, v8, 0x3c000000, v195
	v_mul_f32_e32 v9, 0x4b800000, v8
	v_cmp_gt_f32_e32 vcc, s65, v8
	global_load_dwordx2 v[28:29], v[68:69], off offset:16
	global_load_dwordx2 v[30:31], v[68:69], off offset:32
	global_load_dwordx2 v[46:47], v[68:69], off offset:48
	v_cndmask_b32_e32 v8, v8, v9, vcc
	v_rsq_f32_e32 v10, v8
	v_lshl_add_u64 v[8:9], s[18:19], 0, v[72:73]
	v_lshl_add_u64 v[8:9], v[8:9], 0, v[158:159]
	v_mul_f32_e32 v11, 0x45800000, v10
	v_cndmask_b32_e32 v10, v10, v11, vcc
	v_mul_f32_e32 v10, 0x3f4ccccd, v10
	v_pk_mul_f32 v[48:49], v[48:49], v[10:11] op_sel_hi:[1,0]
	v_pk_mul_f32 v[42:43], v[42:43], v[10:11] op_sel_hi:[1,0]
	v_pk_mul_f32 v[12:13], v[12:13], v[48:49]
	v_pk_mul_f32 v[48:49], v[50:51], v[10:11] op_sel_hi:[1,0]
	v_pk_mul_f32 v[12:13], v[12:13], v[70:71]
	v_pk_mul_f32 v[14:15], v[14:15], v[48:49]
	v_cvt_pk_bf16_f32 v12, v12, v13
	v_pk_mul_f32 v[14:15], v[14:15], v[74:75]
	v_pk_mul_f32 v[50:51], v[80:81], v[10:11] op_sel_hi:[1,0]
	v_cvt_pk_bf16_f32 v13, v14, v15
	global_store_dwordx2 v[8:9], v[12:13], off sc1
	global_load_dwordx4 v[12:15], v156, s[40:41] offset:32
	v_pk_mul_f32 v[44:45], v[44:45], v[10:11] op_sel_hi:[1,0]
	v_pk_mul_f32 v[40:41], v[40:41], v[10:11] op_sel_hi:[1,0]
	v_pk_mul_f32 v[34:35], v[34:35], v[10:11] op_sel_hi:[1,0]
	v_pk_mul_f32 v[32:33], v[32:33], v[10:11] op_sel_hi:[1,0]
	v_pk_mul_f32 v[24:25], v[24:25], v[10:11] op_sel_hi:[1,0]
	v_pk_mul_f32 v[26:27], v[26:27], v[10:11] op_sel_hi:[1,0]
	v_pk_mul_f32 v[22:23], v[22:23], v[10:11] op_sel_hi:[1,0]
	v_pk_mul_f32 v[20:21], v[20:21], v[10:11] op_sel_hi:[1,0]
	v_pk_mul_f32 v[18:19], v[18:19], v[10:11] op_sel_hi:[1,0]
	v_pk_mul_f32 v[16:17], v[16:17], v[10:11] op_sel_hi:[1,0]
	v_pk_mul_f32 v[4:5], v[4:5], v[10:11] op_sel_hi:[1,0]
	v_pk_mul_f32 v[0:1], v[0:1], v[10:11] op_sel_hi:[1,0]
	v_pk_mul_f32 v[6:7], v[6:7], v[10:11] op_sel_hi:[1,0]
	v_pk_mul_f32 v[2:3], v[2:3], v[10:11] op_sel_hi:[1,0]
	s_waitcnt vmcnt(4)
	v_lshlrev_b32_e32 v48, 16, v28
	v_and_b32_e32 v49, 0xffff0000, v28
	v_lshlrev_b32_e32 v28, 16, v29
	v_and_b32_e32 v29, 0xffff0000, v29
	s_waitcnt vmcnt(0)
	v_pk_mul_f32 v[12:13], v[12:13], v[50:51]
	s_nop 0
	v_pk_mul_f32 v[12:13], v[12:13], v[48:49]
	v_pk_mul_f32 v[48:49], v[54:55], v[10:11] op_sel_hi:[1,0]
	v_cvt_pk_bf16_f32 v12, v12, v13
	v_pk_mul_f32 v[14:15], v[14:15], v[48:49]
	v_pk_mul_f32 v[48:49], v[82:83], v[10:11] op_sel_hi:[1,0]
	v_pk_mul_f32 v[14:15], v[14:15], v[28:29]
	v_pk_mul_f32 v[50:51], v[52:53], v[10:11] op_sel_hi:[1,0]
	v_cvt_pk_bf16_f32 v13, v14, v15
	global_store_dwordx2 v[8:9], v[12:13], off offset:16 sc1
	global_load_dwordx4 v[12:15], v156, s[40:41] offset:64
	v_lshlrev_b32_e32 v28, 16, v30
	v_and_b32_e32 v29, 0xffff0000, v30
	v_lshlrev_b32_e32 v30, 16, v31
	v_and_b32_e32 v31, 0xffff0000, v31
	v_pk_mul_f32 v[52:53], v[60:61], v[10:11] op_sel_hi:[1,0]
	v_pk_mul_f32 v[54:55], v[56:57], v[10:11] op_sel_hi:[1,0]
	s_waitcnt vmcnt(0)
	v_pk_mul_f32 v[12:13], v[48:49], v[12:13]
	v_pk_mul_f32 v[14:15], v[50:51], v[14:15]
	v_pk_mul_f32 v[12:13], v[12:13], v[28:29]
	v_pk_mul_f32 v[14:15], v[14:15], v[30:31]
	v_cvt_pk_bf16_f32 v12, v12, v13
	v_cvt_pk_bf16_f32 v13, v14, v15
	global_store_dwordx2 v[8:9], v[12:13], off offset:32 sc1
	global_load_dwordx4 v[12:15], v156, s[40:41] offset:96
	s_nop 0
	global_load_dwordx2 v[28:29], v[68:69], off offset:64
	v_pk_mul_f32 v[48:49], v[86:87], v[10:11] op_sel_hi:[1,0]
	v_pk_mul_f32 v[50:51], v[62:63], v[10:11] op_sel_hi:[1,0]
	v_lshlrev_b32_e32 v30, 16, v46
	v_and_b32_e32 v31, 0xffff0000, v46
	v_lshlrev_b32_e32 v46, 16, v47
	v_and_b32_e32 v47, 0xffff0000, v47
	s_waitcnt vmcnt(1)
	v_pk_mul_f32 v[12:13], v[48:49], v[12:13]
	v_pk_mul_f32 v[14:15], v[50:51], v[14:15]
	v_pk_mul_f32 v[12:13], v[12:13], v[30:31]
	v_pk_mul_f32 v[14:15], v[14:15], v[46:47]
	v_cvt_pk_bf16_f32 v12, v12, v13
	v_cvt_pk_bf16_f32 v13, v14, v15
	global_store_dwordx2 v[8:9], v[12:13], off offset:48 sc1
	global_load_dwordx4 v[12:15], v156, s[40:41] offset:128
	s_nop 0
	global_load_dwordx2 v[30:31], v[68:69], off offset:80
	global_load_dwordx2 v[46:47], v[68:69], off offset:96
	global_load_dwordx2 v[48:49], v[68:69], off offset:112
	s_waitcnt vmcnt(5)
	v_lshlrev_b32_e32 v50, 16, v28
	v_and_b32_e32 v51, 0xffff0000, v28
	v_lshlrev_b32_e32 v28, 16, v29
	v_and_b32_e32 v29, 0xffff0000, v29
	s_waitcnt vmcnt(3)
	v_pk_mul_f32 v[12:13], v[52:53], v[12:13]
	v_pk_mul_f32 v[14:15], v[54:55], v[14:15]
	v_pk_mul_f32 v[12:13], v[12:13], v[50:51]
	v_pk_mul_f32 v[14:15], v[14:15], v[28:29]
	v_cvt_pk_bf16_f32 v12, v12, v13
	v_cvt_pk_bf16_f32 v13, v14, v15
	global_store_dwordx2 v[8:9], v[12:13], off offset:64 sc1
	global_load_dwordx4 v[12:15], v156, s[40:41] offset:160
	v_pk_mul_f32 v[50:51], v[84:85], v[10:11] op_sel_hi:[1,0]
	v_pk_mul_f32 v[52:53], v[58:59], v[10:11] op_sel_hi:[1,0]
	s_waitcnt vmcnt(4)
	v_lshlrev_b32_e32 v28, 16, v30
	v_and_b32_e32 v29, 0xffff0000, v30
	v_lshlrev_b32_e32 v30, 16, v31
	v_and_b32_e32 v31, 0xffff0000, v31
	s_waitcnt vmcnt(0)
	v_pk_mul_f32 v[12:13], v[50:51], v[12:13]
	v_pk_mul_f32 v[14:15], v[52:53], v[14:15]
	v_pk_mul_f32 v[12:13], v[12:13], v[28:29]
	v_pk_mul_f32 v[14:15], v[14:15], v[30:31]
	v_cvt_pk_bf16_f32 v12, v12, v13
	v_cvt_pk_bf16_f32 v13, v14, v15
	global_store_dwordx2 v[8:9], v[12:13], off offset:80 sc1
	global_load_dwordx4 v[12:15], v156, s[40:41] offset:192
	v_lshlrev_b32_e32 v28, 16, v46
	v_and_b32_e32 v29, 0xffff0000, v46
	v_lshlrev_b32_e32 v30, 16, v47
	v_and_b32_e32 v31, 0xffff0000, v47
	v_pk_mul_f32 v[46:47], v[88:89], v[10:11] op_sel_hi:[1,0]
	s_waitcnt vmcnt(0)
	v_pk_mul_f32 v[14:15], v[42:43], v[14:15]
	v_pk_mul_f32 v[12:13], v[46:47], v[12:13]
	v_pk_mul_f32 v[14:15], v[14:15], v[30:31]
	v_pk_mul_f32 v[12:13], v[12:13], v[28:29]
	v_lshlrev_b32_e32 v30, 16, v48
	v_cvt_pk_bf16_f32 v12, v12, v13
	v_cvt_pk_bf16_f32 v13, v14, v15
	global_store_dwordx2 v[8:9], v[12:13], off offset:96 sc1
	global_load_dwordx4 v[12:15], v156, s[40:41] offset:224
	s_nop 0
	global_load_dwordx2 v[28:29], v[68:69], off offset:128
	v_and_b32_e32 v31, 0xffff0000, v48
	v_lshlrev_b32_e32 v42, 16, v49
	v_and_b32_e32 v43, 0xffff0000, v49
	s_waitcnt vmcnt(1)
	v_pk_mul_f32 v[12:13], v[44:45], v[12:13]
	v_pk_mul_f32 v[14:15], v[40:41], v[14:15]
	v_pk_mul_f32 v[12:13], v[12:13], v[30:31]
	v_pk_mul_f32 v[14:15], v[14:15], v[42:43]
	v_cvt_pk_bf16_f32 v12, v12, v13
	v_cvt_pk_bf16_f32 v13, v14, v15
	global_store_dwordx2 v[8:9], v[12:13], off offset:112 sc1
	global_load_dwordx4 v[12:15], v156, s[40:41] offset:256
	s_nop 0
	global_load_dwordx2 v[30:31], v[68:69], off offset:144
	global_load_dwordx2 v[40:41], v[68:69], off offset:160
	global_load_dwordx2 v[42:43], v[68:69], off offset:176
	s_waitcnt vmcnt(5)
	v_lshlrev_b32_e32 v44, 16, v28
	v_and_b32_e32 v45, 0xffff0000, v28
	v_lshlrev_b32_e32 v28, 16, v29
	v_and_b32_e32 v29, 0xffff0000, v29
	s_waitcnt vmcnt(3)
	v_pk_mul_f32 v[12:13], v[34:35], v[12:13]
	v_pk_mul_f32 v[14:15], v[32:33], v[14:15]
	v_pk_mul_f32 v[12:13], v[12:13], v[44:45]
	v_pk_mul_f32 v[14:15], v[14:15], v[28:29]
	v_cvt_pk_bf16_f32 v12, v12, v13
	v_cvt_pk_bf16_f32 v13, v14, v15
	global_store_dwordx2 v[8:9], v[12:13], off offset:128 sc1
	global_load_dwordx4 v[12:15], v156, s[40:41] offset:288
	v_pk_mul_f32 v[32:33], v[38:39], v[10:11] op_sel_hi:[1,0]
	v_pk_mul_f32 v[34:35], v[36:37], v[10:11] op_sel_hi:[1,0]
	s_waitcnt vmcnt(4)
	v_lshlrev_b32_e32 v28, 16, v30
	v_and_b32_e32 v29, 0xffff0000, v30
	v_lshlrev_b32_e32 v30, 16, v31
	v_and_b32_e32 v31, 0xffff0000, v31
	s_waitcnt vmcnt(0)
	v_pk_mul_f32 v[12:13], v[32:33], v[12:13]
	v_pk_mul_f32 v[14:15], v[34:35], v[14:15]
	v_pk_mul_f32 v[12:13], v[12:13], v[28:29]
	v_pk_mul_f32 v[14:15], v[14:15], v[30:31]
	v_cvt_pk_bf16_f32 v12, v12, v13
	v_cvt_pk_bf16_f32 v13, v14, v15
	global_store_dwordx2 v[8:9], v[12:13], off offset:144 sc1
	global_load_dwordx4 v[12:15], v156, s[40:41] offset:320
	v_lshlrev_b32_e32 v28, 16, v40
	v_and_b32_e32 v29, 0xffff0000, v40
	v_lshlrev_b32_e32 v30, 16, v41
	v_and_b32_e32 v31, 0xffff0000, v41
	s_waitcnt vmcnt(0)
	v_pk_mul_f32 v[12:13], v[24:25], v[12:13]
	v_pk_mul_f32 v[14:15], v[26:27], v[14:15]
	v_pk_mul_f32 v[12:13], v[12:13], v[28:29]
	v_pk_mul_f32 v[14:15], v[14:15], v[30:31]
	v_cvt_pk_bf16_f32 v12, v12, v13
	v_cvt_pk_bf16_f32 v13, v14, v15
	global_store_dwordx2 v[8:9], v[12:13], off offset:160 sc1
	global_load_dwordx4 v[12:15], v156, s[40:41] offset:352
	s_nop 0
	global_load_dwordx2 v[24:25], v[68:69], off offset:192
	v_lshlrev_b32_e32 v26, 16, v42
	v_and_b32_e32 v27, 0xffff0000, v42
	v_lshlrev_b32_e32 v28, 16, v43
	v_and_b32_e32 v29, 0xffff0000, v43
	s_waitcnt vmcnt(1)
	v_pk_mul_f32 v[12:13], v[22:23], v[12:13]
	v_pk_mul_f32 v[14:15], v[20:21], v[14:15]
	v_pk_mul_f32 v[12:13], v[12:13], v[26:27]
	v_pk_mul_f32 v[14:15], v[14:15], v[28:29]
	v_cvt_pk_bf16_f32 v12, v12, v13
	v_cvt_pk_bf16_f32 v13, v14, v15
	global_store_dwordx2 v[8:9], v[12:13], off offset:176 sc1
	global_load_dwordx4 v[12:15], v156, s[40:41] offset:384
	s_nop 0
	global_load_dwordx2 v[20:21], v[68:69], off offset:208
	global_load_dwordx2 v[22:23], v[68:69], off offset:224
	global_load_dwordx2 v[26:27], v[68:69], off offset:240
	s_waitcnt vmcnt(5)
	v_lshlrev_b32_e32 v28, 16, v24
	v_and_b32_e32 v29, 0xffff0000, v24
	v_lshlrev_b32_e32 v24, 16, v25
	v_and_b32_e32 v25, 0xffff0000, v25
	s_waitcnt vmcnt(3)
	v_pk_mul_f32 v[12:13], v[18:19], v[12:13]
	v_pk_mul_f32 v[14:15], v[16:17], v[14:15]
	v_pk_mul_f32 v[12:13], v[12:13], v[28:29]
	v_pk_mul_f32 v[14:15], v[14:15], v[24:25]
	v_cvt_pk_bf16_f32 v12, v12, v13
	v_cvt_pk_bf16_f32 v13, v14, v15
	global_store_dwordx2 v[8:9], v[12:13], off offset:192 sc1
	global_load_dwordx4 v[12:15], v156, s[40:41] offset:416
	s_waitcnt vmcnt(4)
	v_lshlrev_b32_e32 v16, 16, v20
	v_and_b32_e32 v17, 0xffff0000, v20
	v_lshlrev_b32_e32 v18, 16, v21
	v_and_b32_e32 v19, 0xffff0000, v21
	s_waitcnt vmcnt(0)
	v_pk_mul_f32 v[4:5], v[4:5], v[12:13]
	v_pk_mul_f32 v[0:1], v[0:1], v[14:15]
	v_pk_mul_f32 v[4:5], v[4:5], v[16:17]
	v_pk_mul_f32 v[0:1], v[0:1], v[18:19]
	v_cvt_pk_bf16_f32 v4, v4, v5
	v_cvt_pk_bf16_f32 v5, v0, v1
	global_store_dwordx2 v[8:9], v[4:5], off offset:208 sc1
	global_load_dwordx4 v[12:15], v156, s[40:41] offset:448
	v_lshlrev_b32_e32 v0, 16, v22
	v_and_b32_e32 v1, 0xffff0000, v22
	v_lshlrev_b32_e32 v4, 16, v23
	v_and_b32_e32 v5, 0xffff0000, v23
	s_waitcnt vmcnt(0)
	v_pk_mul_f32 v[6:7], v[6:7], v[12:13]
	v_pk_mul_f32 v[2:3], v[2:3], v[14:15]
	v_pk_mul_f32 v[0:1], v[6:7], v[0:1]
	v_pk_mul_f32 v[2:3], v[2:3], v[4:5]
	v_cvt_pk_bf16_f32 v0, v0, v1
	v_cvt_pk_bf16_f32 v1, v2, v3
	global_store_dwordx2 v[8:9], v[0:1], off offset:224 sc1
	global_load_dwordx4 v[0:3], v156, s[40:41] offset:480
	v_pk_mul_f32 v[12:13], v[64:65], v[10:11] op_sel_hi:[1,0]
	v_pk_mul_f32 v[10:11], v[66:67], v[10:11] op_sel_hi:[1,0]
	v_lshlrev_b32_e32 v4, 16, v26
	v_and_b32_e32 v5, 0xffff0000, v26
	v_lshlrev_b32_e32 v6, 16, v27
	v_and_b32_e32 v7, 0xffff0000, v27
	s_waitcnt vmcnt(0)
	v_pk_mul_f32 v[0:1], v[12:13], v[0:1]
	v_pk_mul_f32 v[2:3], v[10:11], v[2:3]
	v_pk_mul_f32 v[0:1], v[0:1], v[4:5]
	v_pk_mul_f32 v[2:3], v[2:3], v[6:7]
	v_cvt_pk_bf16_f32 v0, v0, v1
	v_cvt_pk_bf16_f32 v1, v2, v3
	global_store_dwordx2 v[8:9], v[0:1], off offset:240 sc1
	s_branch .LBB0_244

.LBB0_343:
	s_andn2_saveexec_b64 s[6:7], s[6:7]
	s_cbranch_execz .LBB0_363
	s_mov_b64 s[6:7], exec
	s_nop 0
	s_waitcnt lgkmcnt(0)
	s_waitcnt vmcnt(0)
	v_mbcnt_lo_u32_b32 v1, s6, 0
	v_mbcnt_hi_u32_b32 v1, s7, v1
	v_cmp_eq_u32_e32 vcc, 0, v1
	s_and_saveexec_b64 s[20:21], vcc
	s_cbranch_execz .LBB0_346
	s_bcnt1_i32_b64 s6, s[6:7]
	v_mov_b32_e32 v2, 0x4000
	v_mov_b32_e32 v3, s6
	global_atomic_add v2, v2, v3, s[52:53] offset:1024 sc0
